# GDN prep load stage: halo loads batched behind one wait, vmcnt waits regenerated with exact counts
# speedup vs baseline: 1.0123x; 1.0058x over previous
; DI void gdn_prep_phase(const int tid, LAS unsigned char* lds, const P& p, int G, int c) {
;     ...
;             const int ch = ht & 127, th = ht >> 7, isv = th, colq = h * 128 + ch, colkv = 768 + isv * 768 + h * 128 + ch, t0 = th * 32;
;             bf16_t qraw[35], kvraw[67];
;             const bool haloq = (n > 0) || (t0 > 0), halokv = (n > 0);
; #pragma unroll
;             for (int e = 0; e < 3; ++e) { qraw[e] = haloq ? qkv[(tok0 + t0 - 3 + e) * 2304 + colq] : (bf16_t)0; kvraw[e] = halokv ? qkv[(tok0 - 3 + e) * 2304 + colkv] : (bf16_t)0; }
; #pragma unroll
;             for (int e = 0; e < 32; ++e) qraw[3 + e] = qkv[(tok0 + t0 + e) * 2304 + colq];
; #pragma unroll
;             for (int e = 0; e < 64; ++e) kvraw[3 + e] = qkv[(tok0 + e) * 2304 + colkv];
.LBB0_594:
	v_ashrrev_i32_e32 v0, 5, v70
	s_mov_b32 s0, 0x2aaaaaab
	v_mul_hi_i32 v1, v0, s0
	v_lshrrev_b32_e32 v2, 31, v1
	v_add_u32_e32 v2, v1, v2
	v_mul_lo_u32 v1, v2, 6
	v_sub_u32_e32 v0, v0, v1
	v_ashrrev_i32_e32 v3, 31, v2
	v_lshlrev_b32_e32 v1, 7, v0
	v_and_b32_e32 v4, 31, v70
	v_lshlrev_b64 v[2:3], 11, v[2:3]
	v_or_b32_e32 v162, v1, v72
	v_readlane_b32 s26, v250, 7
	v_lshl_or_b32 v2, v4, 6, v2
	v_cmp_ne_u32_e64 s[0:1], 0, v4
	v_ashrrev_i32_e32 v163, 31, v162
	v_readlane_b32 s27, v250, 8
	s_or_b64 s[68:69], s[0:1], s[40:41]
	v_lshl_add_u64 v[8:9], v[76:77], 0, v[2:3]
	v_lshl_add_u64 v[160:161], v[162:163], 1, s[26:27]
	v_mov_b32_e32 v4, 0
	v_mov_b32_e32 v119, 0
	v_mov_b32_e32 v14, 0
	v_mov_b32_e32 v15, 0
	v_mov_b32_e32 v16, 0
	v_mov_b32_e32 v17, 0
	v_mov_b32_e32 v18, 0
	v_mov_b32_e32 v19, 0
	s_and_saveexec_b64 s[70:71], s[68:69]
	s_cbranch_execz .LBB0_596
	v_mad_u64_u32 v[6:7], s[26:27], v8, s56, v[160:161]
	v_mov_b32_e32 v10, v7
	v_mad_u64_u32 v[10:11], s[26:27], v9, s56, v[10:11]
	v_mov_b32_e32 v7, v10
	global_load_ushort v14, v[6:7], off
.LBB0_596:
	s_or_b64 exec, exec, s[70:71]
	v_readlane_b32 s26, v250, 7
	v_add_u32_e32 v180, v73, v1
	v_readlane_b32 s27, v250, 8
	s_nop 1
	v_lshl_add_u64 v[10:11], v[180:181], 1, s[26:27]
	s_and_saveexec_b64 s[70:71], s[0:1]
	s_cbranch_execz .LBB0_598
	v_mad_u64_u32 v[4:5], s[26:27], v2, s56, v[10:11]
	v_mov_b32_e32 v6, v5
	v_mad_u64_u32 v[6:7], s[26:27], v3, s56, v[6:7]
	v_add_co_u32_e32 v4, vcc, 0xffffd000, v4
	s_nop 1
	v_addc_co_u32_e32 v5, vcc, -1, v6, vcc
	global_load_ushort v15, v[4:5], off offset:-1536
.LBB0_598:
	s_or_b64 exec, exec, s[70:71]
	v_mov_b32_e32 v5, 0
	v_mov_b32_e32 v115, 0
	s_and_saveexec_b64 s[70:71], s[68:69]
	s_cbranch_execz .LBB0_600
	v_mad_u64_u32 v[6:7], s[26:27], v8, s56, v[160:161]
	v_mov_b32_e32 v12, v7
	v_mad_u64_u32 v[12:13], s[26:27], v9, s56, v[12:13]
	v_add_co_u32_e32 v6, vcc, 0x1000, v6
	s_nop 1
	v_addc_co_u32_e32 v7, vcc, 0, v12, vcc
	global_load_ushort v16, v[6:7], off offset:512
.LBB0_600:
	s_or_b64 exec, exec, s[70:71]
	s_and_saveexec_b64 s[70:71], s[0:1]
	s_cbranch_execz .LBB0_602
	v_mad_u64_u32 v[6:7], s[26:27], v2, s56, v[10:11]
	v_mov_b32_e32 v12, v7
	v_mad_u64_u32 v[12:13], s[26:27], v3, s56, v[12:13]
	v_add_co_u32_e32 v6, vcc, 0xffffe000, v6
	s_nop 1
	v_addc_co_u32_e32 v7, vcc, -1, v12, vcc
	global_load_ushort v17, v[6:7], off offset:-1024
.LBB0_602:
	s_or_b64 exec, exec, s[70:71]
	v_mov_b32_e32 v7, 0
	v_mov_b32_e32 v117, 0
	s_and_saveexec_b64 s[70:71], s[68:69]
	s_cbranch_execz .LBB0_604
	v_mad_u64_u32 v[12:13], s[26:27], v8, s56, v[160:161]
	v_mov_b32_e32 v6, v13
	v_mad_u64_u32 v[8:9], s[26:27], v9, s56, v[6:7]
	v_add_co_u32_e32 v12, vcc, 0x2000, v12
	s_nop 1
	v_addc_co_u32_e32 v13, vcc, 0, v8, vcc
	global_load_ushort v18, v[12:13], off offset:1024
.LBB0_604:
	s_or_b64 exec, exec, s[70:71]
	v_mad_u64_u32 v[8:9], s[26:27], v2, s56, 0
	v_mov_b32_e32 v6, v9
	v_mad_u64_u32 v[12:13], s[26:27], v3, s56, v[6:7]
	v_mov_b32_e32 v9, v12
	v_lshl_add_u64 v[8:9], v[10:11], 0, v[8:9]
	s_and_saveexec_b64 s[68:69], s[0:1]
	s_cbranch_execz .LBB0_606
	v_add_co_u32_e32 v6, vcc, 0xfffff000, v8
	s_nop 1
	v_addc_co_u32_e32 v7, vcc, -1, v9, vcc
	global_load_ushort v19, v[6:7], off offset:-512
.LBB0_606:
	s_or_b64 exec, exec, s[68:69]
	s_waitcnt vmcnt(0)
	v_lshlrev_b32_e32 v119, 16, v14
	v_lshlrev_b32_e32 v4, 16, v15
	v_lshlrev_b32_e32 v115, 16, v16
	v_lshlrev_b32_e32 v5, 16, v17
	v_lshlrev_b32_e32 v117, 16, v18
	v_lshlrev_b32_e32 v7, 16, v19
	v_or_b32_e32 v1, v2, v74
	v_mad_u64_u32 v[164:165], s[0:1], v1, s56, v[160:161]
	v_or3_b32 v1, v2, v74, 1
	v_mad_u64_u32 v[28:29], s[0:1], v1, s56, v[160:161]
	v_or3_b32 v1, v2, v74, 2
	v_mad_u64_u32 v[10:11], s[0:1], v1, s56, v[160:161]
	v_or3_b32 v1, v2, v74, 3
	v_mad_u64_u32 v[12:13], s[0:1], v1, s56, v[160:161]
	v_or3_b32 v1, v2, v74, 4
	v_mad_u64_u32 v[14:15], s[0:1], v1, s56, v[160:161]
	v_or3_b32 v1, v2, v74, 5
	v_mad_u64_u32 v[16:17], s[0:1], v1, s56, v[160:161]
	v_or3_b32 v1, v2, v74, 6
	v_mad_u64_u32 v[18:19], s[0:1], v1, s56, v[160:161]
	v_or3_b32 v1, v2, v74, 7
	v_mad_u64_u32 v[20:21], s[0:1], v1, s56, v[160:161]
	v_or3_b32 v1, v2, v74, 8
	v_mad_u64_u32 v[22:23], s[0:1], v1, s56, v[160:161]
	v_or3_b32 v1, v2, v74, 9
	v_mad_u64_u32 v[24:25], s[0:1], v1, s56, v[160:161]
	v_or3_b32 v1, v2, v74, 10
	v_mad_u64_u32 v[26:27], s[0:1], v1, s56, v[160:161]
	v_or3_b32 v1, v2, v74, 11
	v_mad_u64_u32 v[30:31], s[0:1], v1, s56, v[160:161]
	v_or3_b32 v1, v2, v74, 12
	v_mad_u64_u32 v[32:33], s[0:1], v1, s56, v[160:161]
	v_or3_b32 v1, v2, v74, 13
	v_mad_u64_u32 v[34:35], s[0:1], v1, s56, v[160:161]
	v_or3_b32 v1, v2, v74, 14
	v_mad_u64_u32 v[36:37], s[0:1], v1, s56, v[160:161]
	v_or3_b32 v1, v2, v74, 15
	v_mad_u64_u32 v[38:39], s[0:1], v1, s56, v[160:161]
	v_or3_b32 v1, v2, v74, 16
	v_mad_u64_u32 v[40:41], s[0:1], v1, s56, v[160:161]
	v_or3_b32 v1, v2, v74, 17
	v_mad_u64_u32 v[42:43], s[0:1], v1, s56, v[160:161]
	v_or3_b32 v1, v2, v74, 18
	v_mad_u64_u32 v[44:45], s[0:1], v1, s56, v[160:161]
	v_or3_b32 v1, v2, v74, 19
	v_mad_u64_u32 v[46:47], s[0:1], v1, s56, v[160:161]
	v_or3_b32 v1, v2, v74, 20
	v_mad_u64_u32 v[48:49], s[0:1], v1, s56, v[160:161]
	v_or3_b32 v1, v2, v74, 21
	v_mad_u64_u32 v[50:51], s[0:1], v1, s56, v[160:161]
	v_or3_b32 v1, v2, v74, 22
	v_mad_u64_u32 v[52:53], s[0:1], v1, s56, v[160:161]
	v_or3_b32 v1, v2, v74, 23
	v_mad_u64_u32 v[54:55], s[0:1], v1, s56, v[160:161]
	v_or3_b32 v1, v2, v74, 24
	v_mad_u64_u32 v[56:57], s[0:1], v1, s56, v[160:161]
	v_or3_b32 v1, v2, v74, 25
	v_mad_u64_u32 v[58:59], s[0:1], v1, s56, v[160:161]
	v_or3_b32 v1, v2, v74, 26
	v_mad_u64_u32 v[60:61], s[0:1], v1, s56, v[160:161]
	v_or3_b32 v1, v2, v74, 27
; DI float bf2f(bf16_t b) { return __uint_as_float(((unsigned)b) << 16); }
; DI float silu_fast(float x) { return x * __builtin_amdgcn_rcpf(1.f + __expf(-x)); }
; DI void gdn_prep_phase(const int tid, LAS unsigned char* lds, const P& p, int G, int c) {
;     ...
;             for (int e = 0; e < 32; ++e) qraw[3 + e] = qkv[(tok0 + t0 + e) * 2304 + colq];
; #pragma unroll
;             for (int e = 0; e < 64; ++e) kvraw[3 + e] = qkv[(tok0 + e) * 2304 + colkv];
;             { const float w0 = convw[colq], w1 = convw[2304 + colq], w2 = convw[4608 + colq], w3 = convw[6912 + colq];
; #pragma unroll
;               for (int e = 0; e < 32; ++e) { const float y = w0 * bf2f(qraw[e]) + w1 * bf2f(qraw[e + 1]) + w2 * bf2f(qraw[e + 2]) + w3 * bf2f(qraw[e + 3]); Qs[(t0 + e) * 136 + ch] = f2bf(silu_fast(y)); } }
	v_mad_u64_u32 v[62:63], s[0:1], v1, s56, v[160:161]
	v_or3_b32 v1, v2, v74, 28
	v_mad_u64_u32 v[64:65], s[0:1], v1, s56, v[160:161]
	v_or3_b32 v1, v2, v74, 29
	v_mad_u64_u32 v[66:67], s[0:1], v1, s56, v[160:161]
	v_or3_b32 v1, v2, v74, 30
	v_mad_u64_u32 v[158:159], s[0:1], v1, s56, v[160:161]
	v_or3_b32 v1, v2, v74, 31
	v_readlane_b32 s68, v253, 52
	v_mad_u64_u32 v[160:161], s[0:1], v1, s56, v[160:161]
	v_readlane_b32 s78, v253, 62
	v_readlane_b32 s79, v253, 63
	s_movk_i32 s1, 0x2000
	v_mul_lo_u32 v6, v3, s56
	v_lshl_add_u64 v[162:163], v[162:163], 2, s[78:79]
	v_add_co_u32_e32 v166, vcc, s1, v162
	v_add_u32_e32 v165, v6, v165
	s_nop 0
	v_addc_co_u32_e32 v167, vcc, 0, v163, vcc
	v_add_u32_e32 v29, v6, v29
	v_add_u32_e32 v11, v6, v11
	v_add_u32_e32 v13, v6, v13
	v_add_u32_e32 v15, v6, v15
	v_add_u32_e32 v17, v6, v17
	v_add_u32_e32 v19, v6, v19
	v_add_u32_e32 v21, v6, v21
	v_add_u32_e32 v23, v6, v23
	v_add_u32_e32 v25, v6, v25
	v_add_u32_e32 v27, v6, v27
	v_add_u32_e32 v31, v6, v31
	v_add_u32_e32 v33, v6, v33
	v_add_u32_e32 v35, v6, v35
	v_add_u32_e32 v37, v6, v37
	v_add_u32_e32 v39, v6, v39
	v_add_u32_e32 v41, v6, v41
	v_add_u32_e32 v43, v6, v43
	v_add_u32_e32 v45, v6, v45
	v_add_u32_e32 v47, v6, v47
	v_add_u32_e32 v49, v6, v49
	v_add_u32_e32 v51, v6, v51
	v_add_u32_e32 v53, v6, v53
	v_add_u32_e32 v55, v6, v55
	v_add_u32_e32 v57, v6, v57
	v_add_u32_e32 v59, v6, v59
	v_add_u32_e32 v61, v6, v61
	v_add_u32_e32 v63, v6, v63
	v_add_u32_e32 v65, v6, v65
	v_add_u32_e32 v67, v6, v67
	v_add_u32_e32 v159, v6, v159
	v_add_u32_e32 v161, v6, v161
	global_load_dword v1, v[162:163], off
	global_load_dword v6, v[166:167], off offset:1024
	s_movk_i32 s26, 0x4000
	v_add_co_u32_e32 v166, vcc, s26, v162
	s_movk_i32 s27, 0x6000
	s_nop 0
	v_addc_co_u32_e32 v167, vcc, 0, v163, vcc
	v_add_co_u32_e32 v162, vcc, s27, v162
	global_load_dword v111, v[166:167], off offset:2048
	s_nop 0
	v_addc_co_u32_e32 v163, vcc, 0, v163, vcc
	global_load_dword v113, v[162:163], off offset:3072
	v_readlane_b32 s69, v253, 53
	v_readlane_b32 s70, v253, 54
	v_readlane_b32 s71, v253, 55
	v_readlane_b32 s72, v253, 56
	v_readlane_b32 s73, v253, 57
	v_readlane_b32 s74, v253, 58
	v_readlane_b32 s75, v253, 59
	v_readlane_b32 s76, v253, 60
	v_readlane_b32 s77, v253, 61
	v_readlane_b32 s80, v254, 0
	v_readlane_b32 s81, v254, 1
	v_readlane_b32 s82, v254, 2
	v_readlane_b32 s83, v254, 3
	s_waitcnt vmcnt(2)
	v_mul_f32_e32 v121, v115, v6
	v_fmac_f32_e32 v121, v119, v1
	global_load_ushort v119, v[164:165], off
	s_waitcnt vmcnt(2)
	v_fmac_f32_e32 v121, v117, v111
	s_waitcnt vmcnt(0)
	v_lshlrev_b32_e32 v171, 16, v119
	v_fmac_f32_e32 v121, v113, v171
	v_mul_f32_e32 v119, 0xbfb8aa3b, v121
	v_exp_f32_e32 v119, v119
	s_nop 0
	v_add_f32_e32 v119, 1.0, v119
	v_rcp_f32_e32 v119, v119
	s_nop 0
	v_mul_f32_e32 v119, v121, v119
	v_cvt_pk_bf16_f32 v177, v119, s0
	s_mov_b32 s0, 0x42000
	global_load_ushort v187, v[28:29], off
	global_load_ushort v186, v[10:11], off
	global_load_ushort v185, v[12:13], off
	global_load_ushort v184, v[14:15], off
	global_load_ushort v183, v[16:17], off
	global_load_ushort v179, v[18:19], off
	global_load_ushort v178, v[20:21], off
	global_load_ushort v176, v[22:23], off
	global_load_ushort v175, v[24:25], off
	global_load_ushort v174, v[26:27], off
	global_load_ushort v173, v[30:31], off
	global_load_ushort v172, v[32:33], off
	global_load_ushort v170, v[34:35], off
	global_load_ushort v169, v[36:37], off
	global_load_ushort v168, v[38:39], off
	global_load_ushort v167, v[40:41], off
	global_load_ushort v166, v[42:43], off
	global_load_ushort v165, v[44:45], off
	global_load_ushort v164, v[46:47], off
	global_load_ushort v162, v[48:49], off
	global_load_ushort v137, v[50:51], off
	global_load_ushort v127, v[52:53], off
	global_load_ushort v121, v[54:55], off
	global_load_ushort v119, v[56:57], off
	global_load_ushort v21, v[58:59], off
	global_load_ushort v20, v[60:61], off
	global_load_ushort v17, v[62:63], off
	global_load_ushort v16, v[64:65], off
	global_load_ushort v14, v[66:67], off
	global_load_ushort v12, v[158:159], off
	global_load_ushort v10, v[160:161], off
	global_load_ushort v11, v[8:9], off
	v_add_co_u32_e32 v18, vcc, s0, v8
	s_mov_b32 s0, 0x43000
	s_nop 0
	v_addc_co_u32_e32 v19, vcc, 0, v9, vcc
	global_load_ushort v13, v[18:19], off offset:1536
	v_add_co_u32_e32 v18, vcc, s0, v8
	s_mov_b32 s0, 0x44000
	s_nop 0
	v_addc_co_u32_e32 v19, vcc, 0, v9, vcc
	global_load_ushort v15, v[18:19], off offset:2048
	v_add_co_u32_e32 v18, vcc, s0, v8
	s_mov_b32 s0, 0x45000
	s_nop 0
	v_addc_co_u32_e32 v19, vcc, 0, v9, vcc
	v_add_co_u32_e32 v22, vcc, s0, v8
	s_mov_b32 s0, 0x46000
	s_nop 0
	v_addc_co_u32_e32 v23, vcc, 0, v9, vcc
	global_load_ushort v18, v[18:19], off offset:2560
	ds_write_b16 v71, v177
	global_load_ushort v19, v[22:23], off offset:3072
	v_add_co_u32_e32 v22, vcc, s0, v8
	s_mov_b32 s0, 0x40000
	s_nop 0
	v_addc_co_u32_e32 v23, vcc, 0, v9, vcc
	v_add_co_u32_e32 v24, vcc, s0, v8
	s_mov_b32 s0, 0x41000
	s_nop 0
	v_addc_co_u32_e32 v25, vcc, 0, v9, vcc
	v_add_co_u32_e32 v26, vcc, s0, v8
	s_mov_b32 s0, 0x3d000
	s_nop 0
	v_addc_co_u32_e32 v27, vcc, 0, v9, vcc
	global_load_ushort v22, v[22:23], off offset:3584
	s_waitcnt vmcnt(11)
	v_lshlrev_b32_e32 v20, 16, v20
	global_load_ushort v24, v[24:25], off offset:512
	s_waitcnt vmcnt(11)
	v_lshlrev_b32_e32 v17, 16, v17
	global_load_ushort v23, v[26:27], off offset:1024
	v_add_co_u32_e32 v26, vcc, s0, v8
	s_mov_b32 s0, 0x3f000
	s_nop 0
	v_addc_co_u32_e32 v27, vcc, 0, v9, vcc
	v_add_co_u32_e32 v28, vcc, s0, v8
	s_mov_b32 s0, 0x3b000
	s_nop 0
	v_addc_co_u32_e32 v29, vcc, 0, v9, vcc
	global_load_ushort v26, v[26:27], off offset:3584
	s_waitcnt vmcnt(11)
; DI void gdn_prep_phase(const int tid, LAS unsigned char* lds, const P& p, int G, int c) {
;     ...
;             for (int e = 0; e < 3; ++e) { qraw[e] = haloq ? qkv[(tok0 + t0 - 3 + e) * 2304 + colq] : (bf16_t)0; kvraw[e] = halokv ? qkv[(tok0 - 3 + e) * 2304 + colkv] : (bf16_t)0; }
; #pragma unroll
;             for (int e = 0; e < 32; ++e) qraw[3 + e] = qkv[(tok0 + t0 + e) * 2304 + colq];
; #pragma unroll
;             for (int e = 0; e < 64; ++e) kvraw[3 + e] = qkv[(tok0 + e) * 2304 + colkv];
	v_lshlrev_b32_e32 v14, 16, v14
	global_load_ushort v25, v[28:29], off
	v_add_co_u32_e32 v28, vcc, s0, v8
	s_mov_b32 s0, 0x3c000
	s_nop 0
	v_addc_co_u32_e32 v29, vcc, 0, v9, vcc
	v_add_co_u32_e32 v30, vcc, s0, v8
	s_mov_b32 s0, 0x39000
	s_nop 0
	v_addc_co_u32_e32 v31, vcc, 0, v9, vcc
	global_load_ushort v27, v[30:31], off offset:3072
	v_add_co_u32_e32 v30, vcc, s0, v8
	s_mov_b32 s0, 0x3a000
	s_nop 0
	v_addc_co_u32_e32 v31, vcc, 0, v9, vcc
	v_add_co_u32_e32 v32, vcc, s0, v8
	s_mov_b32 s0, 0x37000
	s_nop 0
	v_addc_co_u32_e32 v33, vcc, 0, v9, vcc
	global_load_ushort v28, v[28:29], off offset:2560
	s_waitcnt vmcnt(13)
	v_lshlrev_b32_e32 v12, 16, v12
	global_load_ushort v30, v[30:31], off offset:1536
	s_waitcnt vmcnt(8)
	v_lshlrev_b32_e32 v19, 16, v19
	global_load_ushort v29, v[32:33], off offset:2048
	v_add_co_u32_e32 v32, vcc, s0, v8
	s_mov_b32 s0, 0x38000
	s_nop 0
	v_addc_co_u32_e32 v33, vcc, 0, v9, vcc
	v_add_co_u32_e32 v34, vcc, s0, v8
	s_mov_b32 s0, 0x34000
	s_nop 0
	v_addc_co_u32_e32 v35, vcc, 0, v9, vcc
	global_load_ushort v32, v[32:33], off offset:512
	s_waitcnt vmcnt(7)
	v_lshlrev_b32_e32 v23, 16, v23
	global_load_ushort v31, v[34:35], off offset:1024
	v_add_co_u32_e32 v34, vcc, s0, v8
	s_mov_b32 s0, 0x36000
	s_nop 0
	v_addc_co_u32_e32 v35, vcc, 0, v9, vcc
	v_add_co_u32_e32 v36, vcc, s0, v8
	s_mov_b32 s0, 0x32000
	s_nop 0
	v_addc_co_u32_e32 v37, vcc, 0, v9, vcc
	global_load_ushort v34, v[34:35], off offset:3584
	s_waitcnt vmcnt(7)
	v_lshlrev_b32_e32 v25, 16, v25
	global_load_ushort v33, v[36:37], off
	v_add_co_u32_e32 v36, vcc, s0, v8
	s_mov_b32 s0, 0x33000
	s_nop 0
	v_addc_co_u32_e32 v37, vcc, 0, v9, vcc
	v_add_co_u32_e32 v38, vcc, s0, v8
	s_mov_b32 s0, 0x30000
	s_nop 0
	v_addc_co_u32_e32 v39, vcc, 0, v9, vcc
	global_load_ushort v35, v[38:39], off offset:3072
	v_add_co_u32_e32 v38, vcc, s0, v8
	s_mov_b32 s0, 0x31000
	s_nop 0
	v_addc_co_u32_e32 v39, vcc, 0, v9, vcc
	v_add_co_u32_e32 v40, vcc, s0, v8
	s_mov_b32 s0, 0x2e000
	s_nop 0
	v_addc_co_u32_e32 v41, vcc, 0, v9, vcc
	global_load_ushort v36, v[36:37], off offset:2560
	s_waitcnt vmcnt(9)
	v_lshlrev_b32_e32 v27, 16, v27
	global_load_ushort v38, v[38:39], off offset:1536
	s_waitcnt vmcnt(7)
	v_lshlrev_b32_e32 v29, 16, v29
	global_load_ushort v37, v[40:41], off offset:2048
	v_add_co_u32_e32 v40, vcc, s0, v8
	s_mov_b32 s0, 0x2f000
	s_nop 0
	v_addc_co_u32_e32 v41, vcc, 0, v9, vcc
	v_add_co_u32_e32 v42, vcc, s0, v8
	s_mov_b32 s0, 0x2b000
	s_nop 0
	v_addc_co_u32_e32 v43, vcc, 0, v9, vcc
	global_load_ushort v40, v[40:41], off offset:512
	s_waitcnt vmcnt(7)
	v_lshlrev_b32_e32 v31, 16, v31
	global_load_ushort v39, v[42:43], off offset:1024
	v_add_co_u32_e32 v42, vcc, s0, v8
	s_mov_b32 s0, 0x2d000
	s_nop 0
	v_addc_co_u32_e32 v43, vcc, 0, v9, vcc
	v_add_co_u32_e32 v44, vcc, s0, v8
	s_mov_b32 s0, 0x29000
	s_nop 0
	v_addc_co_u32_e32 v45, vcc, 0, v9, vcc
	global_load_ushort v42, v[42:43], off offset:3584
	s_waitcnt vmcnt(7)
	v_lshlrev_b32_e32 v33, 16, v33
	global_load_ushort v41, v[44:45], off
	v_add_co_u32_e32 v44, vcc, s0, v8
	s_mov_b32 s0, 0x2a000
	s_nop 0
	v_addc_co_u32_e32 v45, vcc, 0, v9, vcc
	v_add_co_u32_e32 v46, vcc, s0, v8
	s_mov_b32 s0, 0x27000
	s_nop 0
	v_addc_co_u32_e32 v47, vcc, 0, v9, vcc
	global_load_ushort v43, v[46:47], off offset:3072
	v_add_co_u32_e32 v46, vcc, s0, v8
	s_mov_b32 s0, 0x28000
	s_nop 0
	v_addc_co_u32_e32 v47, vcc, 0, v9, vcc
	v_add_co_u32_e32 v48, vcc, s0, v8
	s_mov_b32 s0, 0x25000
	s_nop 0
	v_addc_co_u32_e32 v49, vcc, 0, v9, vcc
	global_load_ushort v44, v[44:45], off offset:2560
	s_waitcnt vmcnt(9)
	v_lshlrev_b32_e32 v35, 16, v35
	global_load_ushort v46, v[46:47], off offset:1536
	s_waitcnt vmcnt(7)
	v_lshlrev_b32_e32 v37, 16, v37
	global_load_ushort v45, v[48:49], off offset:2048
	v_add_co_u32_e32 v48, vcc, s0, v8
	s_mov_b32 s0, 0x26000
	s_nop 0
	v_addc_co_u32_e32 v49, vcc, 0, v9, vcc
	v_add_co_u32_e32 v50, vcc, s0, v8
	s_mov_b32 s0, 0x22000
	s_nop 0
	v_addc_co_u32_e32 v51, vcc, 0, v9, vcc
	global_load_ushort v48, v[48:49], off offset:512
	s_waitcnt vmcnt(7)
	v_lshlrev_b32_e32 v39, 16, v39
	global_load_ushort v47, v[50:51], off offset:1024
	v_add_co_u32_e32 v50, vcc, s0, v8
	s_mov_b32 s0, 0x24000
	s_nop 0
	v_addc_co_u32_e32 v51, vcc, 0, v9, vcc
	v_add_co_u32_e32 v52, vcc, s0, v8
	s_mov_b32 s0, 0x20000
	s_nop 0
	v_addc_co_u32_e32 v53, vcc, 0, v9, vcc
	global_load_ushort v50, v[50:51], off offset:3584
	s_waitcnt vmcnt(7)
	v_lshlrev_b32_e32 v41, 16, v41
	global_load_ushort v49, v[52:53], off
	v_add_co_u32_e32 v52, vcc, s0, v8
	s_mov_b32 s0, 0x21000
	s_nop 0
	v_addc_co_u32_e32 v53, vcc, 0, v9, vcc
	v_add_co_u32_e32 v54, vcc, s0, v8
	s_mov_b32 s0, 0x1e000
	s_nop 0
	v_addc_co_u32_e32 v55, vcc, 0, v9, vcc
	global_load_ushort v51, v[54:55], off offset:3072
	v_add_co_u32_e32 v54, vcc, s0, v8
	s_mov_b32 s0, 0x1f000
	s_nop 0
	v_addc_co_u32_e32 v55, vcc, 0, v9, vcc
	v_add_co_u32_e32 v56, vcc, s0, v8
	s_mov_b32 s0, 0x1c000
	s_nop 0
	v_addc_co_u32_e32 v57, vcc, 0, v9, vcc
	global_load_ushort v52, v[52:53], off offset:2560
	s_waitcnt vmcnt(9)
	v_lshlrev_b32_e32 v43, 16, v43
	global_load_ushort v54, v[54:55], off offset:1536
	s_waitcnt vmcnt(7)
	v_lshlrev_b32_e32 v45, 16, v45
	global_load_ushort v53, v[56:57], off offset:2048
	v_add_co_u32_e32 v56, vcc, s0, v8
	s_mov_b32 s0, 0x1d000
	s_nop 0
	v_addc_co_u32_e32 v57, vcc, 0, v9, vcc
	v_add_co_u32_e32 v58, vcc, s0, v8
	s_mov_b32 s0, 0x19000
	s_nop 0
	v_addc_co_u32_e32 v59, vcc, 0, v9, vcc
	global_load_ushort v56, v[56:57], off offset:512
	s_waitcnt vmcnt(7)
; DI float bf2f(bf16_t b) { return __uint_as_float(((unsigned)b) << 16); }
; DI float silu_fast(float x) { return x * __builtin_amdgcn_rcpf(1.f + __expf(-x)); }
; DI void gdn_prep_phase(const int tid, LAS unsigned char* lds, const P& p, int G, int c) {
;     ...
;             for (int e = 0; e < 3; ++e) { qraw[e] = haloq ? qkv[(tok0 + t0 - 3 + e) * 2304 + colq] : (bf16_t)0; kvraw[e] = halokv ? qkv[(tok0 - 3 + e) * 2304 + colkv] : (bf16_t)0; }
; #pragma unroll
;             for (int e = 0; e < 32; ++e) qraw[3 + e] = qkv[(tok0 + t0 + e) * 2304 + colq];
; #pragma unroll
;             for (int e = 0; e < 64; ++e) kvraw[3 + e] = qkv[(tok0 + e) * 2304 + colkv];
;             { const float w0 = convw[colq], w1 = convw[2304 + colq], w2 = convw[4608 + colq], w3 = convw[6912 + colq];
; #pragma unroll
;               for (int e = 0; e < 32; ++e) { const float y = w0 * bf2f(qraw[e]) + w1 * bf2f(qraw[e + 1]) + w2 * bf2f(qraw[e + 2]) + w3 * bf2f(qraw[e + 3]); Qs[(t0 + e) * 136 + ch] = f2bf(silu_fast(y)); } }
	v_lshlrev_b32_e32 v47, 16, v47
	global_load_ushort v55, v[58:59], off offset:1024
	v_add_co_u32_e32 v58, vcc, s0, v8
	s_mov_b32 s0, 0x1b000
	s_nop 0
	v_addc_co_u32_e32 v59, vcc, 0, v9, vcc
	v_add_co_u32_e32 v60, vcc, s0, v8
	s_mov_b32 s0, 0x17000
	s_nop 0
	v_addc_co_u32_e32 v61, vcc, 0, v9, vcc
	global_load_ushort v58, v[58:59], off offset:3584
	s_waitcnt vmcnt(7)
	v_lshlrev_b32_e32 v49, 16, v49
	global_load_ushort v57, v[60:61], off
	v_add_co_u32_e32 v60, vcc, s0, v8
	s_mov_b32 s0, 0x18000
	s_nop 0
	v_addc_co_u32_e32 v61, vcc, 0, v9, vcc
	v_add_co_u32_e32 v62, vcc, s0, v8
	s_mov_b32 s0, 0x15000
	s_nop 0
	v_addc_co_u32_e32 v63, vcc, 0, v9, vcc
	global_load_ushort v59, v[62:63], off offset:3072
	v_add_co_u32_e32 v62, vcc, s0, v8
	s_mov_b32 s0, 0x16000
	s_nop 0
	v_addc_co_u32_e32 v63, vcc, 0, v9, vcc
	v_add_co_u32_e32 v64, vcc, s0, v8
	s_mov_b32 s0, 0x13000
	s_nop 0
	v_addc_co_u32_e32 v65, vcc, 0, v9, vcc
	global_load_ushort v60, v[60:61], off offset:2560
	s_waitcnt vmcnt(9)
	v_lshlrev_b32_e32 v51, 16, v51
	global_load_ushort v62, v[62:63], off offset:1536
	s_waitcnt vmcnt(7)
	v_lshlrev_b32_e32 v53, 16, v53
	global_load_ushort v61, v[64:65], off offset:2048
	v_add_co_u32_e32 v64, vcc, s0, v8
	s_mov_b32 s0, 0x14000
	s_nop 0
	v_addc_co_u32_e32 v65, vcc, 0, v9, vcc
	v_add_co_u32_e32 v66, vcc, s0, v8
	s_mov_b32 s0, 0x10000
	s_nop 0
	v_addc_co_u32_e32 v67, vcc, 0, v9, vcc
	global_load_ushort v64, v[64:65], off offset:512
	s_waitcnt vmcnt(7)
	v_lshlrev_b32_e32 v55, 16, v55
	global_load_ushort v63, v[66:67], off offset:1024
	v_add_co_u32_e32 v66, vcc, s0, v8
	s_mov_b32 s0, 0x12000
	s_nop 0
	v_addc_co_u32_e32 v67, vcc, 0, v9, vcc
	v_add_co_u32_e32 v158, vcc, s0, v8
	s_mov_b32 s0, 0xe000
	s_nop 0
	v_addc_co_u32_e32 v159, vcc, 0, v9, vcc
	global_load_ushort v66, v[66:67], off offset:3584
	s_waitcnt vmcnt(7)
	v_lshlrev_b32_e32 v57, 16, v57
	global_load_ushort v65, v[158:159], off
	v_add_co_u32_e32 v158, vcc, s0, v8
	s_mov_b32 s0, 0xf000
	s_nop 0
	v_addc_co_u32_e32 v159, vcc, 0, v9, vcc
	global_load_ushort v123, v[158:159], off offset:2560
	v_add_co_u32_e32 v158, vcc, s0, v8
	s_mov_b32 s0, 0xc000
	s_nop 0
	v_addc_co_u32_e32 v159, vcc, 0, v9, vcc
	global_load_ushort v67, v[158:159], off offset:3072
	v_add_co_u32_e32 v158, vcc, s0, v8
	s_mov_b32 s0, 0xd000
	s_nop 0
	v_addc_co_u32_e32 v159, vcc, 0, v9, vcc
	global_load_ushort v125, v[158:159], off offset:1536
	v_add_co_u32_e32 v158, vcc, s0, v8
	s_mov_b32 s0, 0xa000
	s_nop 0
	v_addc_co_u32_e32 v159, vcc, 0, v9, vcc
	global_load_ushort v129, v[158:159], off offset:2048
	v_add_co_u32_e32 v158, vcc, s0, v8
	s_mov_b32 s0, 0xb000
	s_nop 0
	v_addc_co_u32_e32 v159, vcc, 0, v9, vcc
	global_load_ushort v131, v[158:159], off offset:512
	v_add_co_u32_e32 v158, vcc, s0, v8
	s_movk_i32 s0, 0x7000
	s_nop 0
	v_addc_co_u32_e32 v159, vcc, 0, v9, vcc
	global_load_ushort v133, v[158:159], off offset:1024
	v_add_co_u32_e32 v158, vcc, s0, v8
	s_mov_b32 s0, 0x9000
	s_nop 0
	v_addc_co_u32_e32 v159, vcc, 0, v9, vcc
	global_load_ushort v135, v[158:159], off offset:3584
	v_add_co_u32_e32 v158, vcc, s0, v8
	s_movk_i32 s0, 0x5000
	s_nop 0
	v_addc_co_u32_e32 v159, vcc, 0, v9, vcc
	global_load_ushort v139, v[158:159], off
	v_add_co_u32_e32 v158, vcc, s0, v8
	s_movk_i32 s0, 0x3000
	s_nop 0
	v_addc_co_u32_e32 v159, vcc, 0, v9, vcc
	global_load_ushort v141, v[158:159], off offset:2560
	v_add_co_u32_e32 v158, vcc, s27, v8
	s_waitcnt vmcnt(13)
	v_lshlrev_b32_e32 v61, 16, v61
	v_addc_co_u32_e32 v159, vcc, 0, v9, vcc
	v_add_co_u32_e32 v160, vcc, s0, v8
	global_load_ushort v158, v[158:159], off offset:3072
	s_nop 0
	v_addc_co_u32_e32 v161, vcc, 0, v9, vcc
	global_load_ushort v159, v[160:161], off offset:1536
	v_add_co_u32_e32 v160, vcc, s26, v8
	s_movk_i32 s0, 0x1000
	s_nop 0
	v_addc_co_u32_e32 v161, vcc, 0, v9, vcc
	v_add_co_u32_e32 v188, vcc, s0, v8
	global_load_ushort v161, v[160:161], off offset:2048
	s_nop 0
	v_addc_co_u32_e32 v189, vcc, 0, v9, vcc
	v_add_co_u32_e32 v8, vcc, s1, v8
	s_waitcnt vmcnt(14)
	v_lshlrev_b32_e32 v63, 16, v63
	v_addc_co_u32_e32 v9, vcc, 0, v9, vcc
	global_load_ushort v163, v[8:9], off offset:1024
	v_mul_f32_e32 v8, v117, v6
	v_fmac_f32_e32 v8, v115, v1
	v_fmac_f32_e32 v8, v111, v171
	v_lshlrev_b32_e32 v9, 16, v187
	v_fmac_f32_e32 v8, v113, v9
	v_mul_f32_e32 v115, 0xbfb8aa3b, v8
	v_exp_f32_e32 v115, v115
	global_load_ushort v160, v[188:189], off offset:512
	s_waitcnt vmcnt(14)
	v_lshlrev_b32_e32 v65, 16, v65
	v_lshlrev_b32_e32 v59, 16, v59
	v_add_f32_e32 v115, 1.0, v115
	v_rcp_f32_e32 v115, v115
	s_waitcnt vmcnt(12)
	v_lshlrev_b32_e32 v67, 16, v67
	v_mul_f32_e32 v8, v8, v115
	v_cvt_pk_bf16_f32 v8, v8, s0
	ds_write_b16 v71, v8 offset:272
	v_mul_f32_e32 v8, v6, v171
	v_fmac_f32_e32 v8, v117, v1
	v_fmac_f32_e32 v8, v111, v9
	v_lshlrev_b32_e32 v115, 16, v186
	v_fmac_f32_e32 v8, v113, v115
	v_mul_f32_e32 v117, 0xbfb8aa3b, v8
	v_exp_f32_e32 v117, v117
	s_waitcnt vmcnt(0)
; DI float bf2f(bf16_t b) { return __uint_as_float(((unsigned)b) << 16); }
; DI float silu_fast(float x) { return x * __builtin_amdgcn_rcpf(1.f + __expf(-x)); }
; DI void gdn_prep_phase(const int tid, LAS unsigned char* lds, const P& p, int G, int c) {
;     ...
;             { const float w0 = convw[colq], w1 = convw[2304 + colq], w2 = convw[4608 + colq], w3 = convw[6912 + colq];
; #pragma unroll
;               for (int e = 0; e < 32; ++e) { const float y = w0 * bf2f(qraw[e]) + w1 * bf2f(qraw[e + 1]) + w2 * bf2f(qraw[e + 2]) + w3 * bf2f(qraw[e + 3]); Qs[(t0 + e) * 136 + ch] = f2bf(silu_fast(y)); } }
	v_lshlrev_b32_e32 v160, 16, v160
	v_add_f32_e32 v117, 1.0, v117
	v_rcp_f32_e32 v117, v117
	s_nop 0
	v_mul_f32_e32 v8, v8, v117
	v_cvt_pk_bf16_f32 v8, v8, s0
	ds_write_b16 v71, v8 offset:544
	v_mul_f32_e32 v8, v6, v9
	v_fmac_f32_e32 v8, v1, v171
	v_fmac_f32_e32 v8, v111, v115
	v_lshlrev_b32_e32 v117, 16, v185
	v_fmac_f32_e32 v8, v113, v117
	v_mul_f32_e32 v171, 0xbfb8aa3b, v8
	v_exp_f32_e32 v171, v171
	s_nop 0
	v_add_f32_e32 v171, 1.0, v171
	v_rcp_f32_e32 v171, v171
	s_nop 0
	v_mul_f32_e32 v8, v8, v171
	v_cvt_pk_bf16_f32 v8, v8, s0
	ds_write_b16 v71, v8 offset:816
	v_mul_f32_e32 v8, v6, v115
	v_fmac_f32_e32 v8, v1, v9
	v_fmac_f32_e32 v8, v111, v117
	v_lshlrev_b32_e32 v9, 16, v184
	v_fmac_f32_e32 v8, v113, v9
	v_mul_f32_e32 v171, 0xbfb8aa3b, v8
	v_exp_f32_e32 v171, v171
	s_nop 0
	v_add_f32_e32 v171, 1.0, v171
	v_rcp_f32_e32 v171, v171
	s_nop 0
	v_mul_f32_e32 v8, v8, v171
	v_cvt_pk_bf16_f32 v8, v8, s0
	ds_write_b16 v71, v8 offset:1088
	v_mul_f32_e32 v8, v6, v117
	v_fmac_f32_e32 v8, v1, v115
	v_fmac_f32_e32 v8, v111, v9
	v_lshlrev_b32_e32 v115, 16, v183
	v_fmac_f32_e32 v8, v113, v115
	v_mul_f32_e32 v171, 0xbfb8aa3b, v8
	v_exp_f32_e32 v171, v171
	s_nop 0
	v_add_f32_e32 v171, 1.0, v171
	v_rcp_f32_e32 v171, v171
	s_nop 0
	v_mul_f32_e32 v8, v8, v171
	v_cvt_pk_bf16_f32 v8, v8, s0
	ds_write_b16 v71, v8 offset:1360
	v_mul_f32_e32 v8, v6, v9
	v_fmac_f32_e32 v8, v1, v117
	v_fmac_f32_e32 v8, v111, v115
	v_lshlrev_b32_e32 v117, 16, v179
	v_fmac_f32_e32 v8, v113, v117
	v_mul_f32_e32 v171, 0xbfb8aa3b, v8
	v_exp_f32_e32 v171, v171
	s_nop 0
	v_add_f32_e32 v171, 1.0, v171
	v_rcp_f32_e32 v171, v171
	s_nop 0
	v_mul_f32_e32 v8, v8, v171
	v_cvt_pk_bf16_f32 v8, v8, s0
	ds_write_b16 v71, v8 offset:1632
	v_mul_f32_e32 v8, v6, v115
	v_fmac_f32_e32 v8, v1, v9
	v_fmac_f32_e32 v8, v111, v117
	v_lshlrev_b32_e32 v9, 16, v178
	v_fmac_f32_e32 v8, v113, v9
	v_mul_f32_e32 v171, 0xbfb8aa3b, v8
	v_exp_f32_e32 v171, v171
	s_nop 0
	v_add_f32_e32 v171, 1.0, v171
	v_rcp_f32_e32 v171, v171
	s_nop 0
	v_mul_f32_e32 v8, v8, v171
	v_cvt_pk_bf16_f32 v8, v8, s0
	ds_write_b16 v71, v8 offset:1904
	v_mul_f32_e32 v8, v6, v117
	v_fmac_f32_e32 v8, v1, v115
	v_fmac_f32_e32 v8, v111, v9
	v_lshlrev_b32_e32 v115, 16, v176
	v_fmac_f32_e32 v8, v113, v115
	v_mul_f32_e32 v171, 0xbfb8aa3b, v8
	v_exp_f32_e32 v171, v171
	s_nop 0
	v_add_f32_e32 v171, 1.0, v171
	v_rcp_f32_e32 v171, v171
	s_nop 0
	v_mul_f32_e32 v8, v8, v171
	v_cvt_pk_bf16_f32 v8, v8, s0
	ds_write_b16 v71, v8 offset:2176
	v_mul_f32_e32 v8, v6, v9
	v_fmac_f32_e32 v8, v1, v117
	v_fmac_f32_e32 v8, v111, v115
	v_lshlrev_b32_e32 v117, 16, v175
	v_fmac_f32_e32 v8, v113, v117
	v_mul_f32_e32 v171, 0xbfb8aa3b, v8
	v_exp_f32_e32 v171, v171
	v_lshlrev_b32_e32 v175, 16, v161
	v_lshlrev_b32_e32 v161, 16, v163
	v_add_f32_e32 v171, 1.0, v171
	v_rcp_f32_e32 v171, v171
	s_nop 0
	v_mul_f32_e32 v8, v8, v171
	v_cvt_pk_bf16_f32 v8, v8, s0
	ds_write_b16 v71, v8 offset:2448
	v_mul_f32_e32 v8, v6, v115
	v_fmac_f32_e32 v8, v1, v9
	v_fmac_f32_e32 v8, v111, v117
	v_lshlrev_b32_e32 v9, 16, v174
	v_fmac_f32_e32 v8, v113, v9
	v_mul_f32_e32 v171, 0xbfb8aa3b, v8
	v_exp_f32_e32 v171, v171
	v_lshlrev_b32_e32 v174, 16, v159
	v_add_f32_e32 v171, 1.0, v171
	v_rcp_f32_e32 v171, v171
	s_nop 0
	v_mul_f32_e32 v8, v8, v171
	v_cvt_pk_bf16_f32 v8, v8, s0
	ds_write_b16 v71, v8 offset:2720
	v_mul_f32_e32 v8, v6, v117
	v_fmac_f32_e32 v8, v1, v115
	v_fmac_f32_e32 v8, v111, v9
	v_lshlrev_b32_e32 v115, 16, v173
	v_fmac_f32_e32 v8, v113, v115
	v_mul_f32_e32 v171, 0xbfb8aa3b, v8
	v_exp_f32_e32 v171, v171
	v_lshlrev_b32_e32 v173, 16, v158
	v_add_f32_e32 v171, 1.0, v171
	v_rcp_f32_e32 v171, v171
	s_nop 0
	v_mul_f32_e32 v8, v8, v171
	v_cvt_pk_bf16_f32 v8, v8, s0
	ds_write_b16 v71, v8 offset:2992
	v_mul_f32_e32 v8, v6, v9
	v_fmac_f32_e32 v8, v1, v117
	v_fmac_f32_e32 v8, v111, v115
	v_lshlrev_b32_e32 v117, 16, v172
	v_fmac_f32_e32 v8, v113, v117
	v_mul_f32_e32 v171, 0xbfb8aa3b, v8
	v_exp_f32_e32 v171, v171
	v_lshlrev_b32_e32 v172, 16, v141
	v_add_f32_e32 v171, 1.0, v171
	v_rcp_f32_e32 v171, v171
	s_nop 0
	v_mul_f32_e32 v8, v8, v171
	v_cvt_pk_bf16_f32 v8, v8, s0
	ds_write_b16 v71, v8 offset:3264
	v_mul_f32_e32 v8, v6, v115
	v_fmac_f32_e32 v8, v1, v9
	v_fmac_f32_e32 v8, v111, v117
	v_lshlrev_b32_e32 v9, 16, v170
	v_fmac_f32_e32 v8, v113, v9
	v_mul_f32_e32 v170, 0xbfb8aa3b, v8
	v_exp_f32_e32 v170, v170
	v_lshlrev_b32_e32 v171, 16, v139
	v_add_f32_e32 v170, 1.0, v170
	v_rcp_f32_e32 v170, v170
	s_nop 0
	v_mul_f32_e32 v8, v8, v170
	v_cvt_pk_bf16_f32 v8, v8, s0
	ds_write_b16 v71, v8 offset:3536
	v_mul_f32_e32 v8, v6, v117
	v_fmac_f32_e32 v8, v1, v115
	v_fmac_f32_e32 v8, v111, v9
	v_lshlrev_b32_e32 v115, 16, v169
	v_fmac_f32_e32 v8, v113, v115
	v_mul_f32_e32 v169, 0xbfb8aa3b, v8
	v_exp_f32_e32 v169, v169
	v_lshlrev_b32_e32 v170, 16, v135
	v_add_f32_e32 v169, 1.0, v169
	v_rcp_f32_e32 v169, v169
	s_nop 0
	v_mul_f32_e32 v8, v8, v169
	v_cvt_pk_bf16_f32 v8, v8, s0
	ds_write_b16 v71, v8 offset:3808
	v_mul_f32_e32 v8, v6, v9
	v_fmac_f32_e32 v8, v1, v117
	v_fmac_f32_e32 v8, v111, v115
	v_lshlrev_b32_e32 v117, 16, v168
	v_fmac_f32_e32 v8, v113, v117
	v_mul_f32_e32 v168, 0xbfb8aa3b, v8
	v_exp_f32_e32 v168, v168
	v_lshlrev_b32_e32 v169, 16, v11
	v_add_f32_e32 v168, 1.0, v168
	v_rcp_f32_e32 v168, v168
	s_nop 0
	v_mul_f32_e32 v8, v8, v168
	v_cvt_pk_bf16_f32 v8, v8, s0
	ds_write_b16 v71, v8 offset:4080
	v_mul_f32_e32 v8, v6, v115
	v_fmac_f32_e32 v8, v1, v9
	v_fmac_f32_e32 v8, v111, v117
	v_lshlrev_b32_e32 v9, 16, v167
	v_fmac_f32_e32 v8, v113, v9
	v_mul_f32_e32 v167, 0xbfb8aa3b, v8
	v_exp_f32_e32 v167, v167
	v_mov_b32_e32 v168, v7
	v_add_f32_e32 v167, 1.0, v167
	v_rcp_f32_e32 v167, v167
	s_nop 0
	v_mul_f32_e32 v8, v8, v167
; DI float bf2f(bf16_t b) { return __uint_as_float(((unsigned)b) << 16); }
; DI float silu_fast(float x) { return x * __builtin_amdgcn_rcpf(1.f + __expf(-x)); }
; DI void gdn_prep_phase(const int tid, LAS unsigned char* lds, const P& p, int G, int c) {
;     ...
;             { const float w0 = convw[colq], w1 = convw[2304 + colq], w2 = convw[4608 + colq], w3 = convw[6912 + colq];
; #pragma unroll
;               for (int e = 0; e < 32; ++e) { const float y = w0 * bf2f(qraw[e]) + w1 * bf2f(qraw[e + 1]) + w2 * bf2f(qraw[e + 2]) + w3 * bf2f(qraw[e + 3]); Qs[(t0 + e) * 136 + ch] = f2bf(silu_fast(y)); } }
;             { const float w0 = convw[colkv], w1 = convw[2304 + colkv], w2 = convw[4608 + colkv], w3 = convw[6912 + colkv];
	v_cvt_pk_bf16_f32 v8, v8, s0
	ds_write_b16 v71, v8 offset:4352
	v_mul_f32_e32 v8, v6, v117
	v_fmac_f32_e32 v8, v1, v115
	v_fmac_f32_e32 v8, v111, v9
	v_lshlrev_b32_e32 v115, 16, v166
	v_fmac_f32_e32 v8, v113, v115
	v_mul_f32_e32 v166, 0xbfb8aa3b, v8
	v_exp_f32_e32 v166, v166
	v_lshlrev_b32_e32 v167, 16, v129
	v_add_f32_e32 v166, 1.0, v166
	v_rcp_f32_e32 v166, v166
	s_nop 0
	v_mul_f32_e32 v8, v8, v166
	v_cvt_pk_bf16_f32 v8, v8, s0
	ds_write_b16 v71, v8 offset:4624
	v_mul_f32_e32 v8, v6, v9
	v_fmac_f32_e32 v8, v1, v117
	v_fmac_f32_e32 v8, v111, v115
	v_lshlrev_b32_e32 v117, 16, v165
	v_fmac_f32_e32 v8, v113, v117
	v_mul_f32_e32 v165, 0xbfb8aa3b, v8
	v_exp_f32_e32 v165, v165
	v_lshlrev_b32_e32 v166, 16, v125
	v_add_f32_e32 v165, 1.0, v165
	v_rcp_f32_e32 v165, v165
	s_nop 0
	v_mul_f32_e32 v8, v8, v165
	v_cvt_pk_bf16_f32 v8, v8, s0
	ds_write_b16 v71, v8 offset:4896
	v_mul_f32_e32 v8, v6, v115
	v_fmac_f32_e32 v8, v1, v9
	v_fmac_f32_e32 v8, v111, v117
	v_lshlrev_b32_e32 v9, 16, v164
	v_fmac_f32_e32 v8, v113, v9
	v_mul_f32_e32 v164, 0xbfb8aa3b, v8
	v_exp_f32_e32 v164, v164
	v_lshlrev_b32_e32 v165, 16, v133
	v_add_f32_e32 v164, 1.0, v164
	v_rcp_f32_e32 v164, v164
	s_nop 0
	v_mul_f32_e32 v8, v8, v164
	v_cvt_pk_bf16_f32 v8, v8, s0
	ds_write_b16 v71, v8 offset:5168
	v_mul_f32_e32 v8, v6, v117
	v_fmac_f32_e32 v8, v1, v115
	v_fmac_f32_e32 v8, v111, v9
	v_lshlrev_b32_e32 v115, 16, v162
	v_fmac_f32_e32 v8, v113, v115
	v_mul_f32_e32 v162, 0xbfb8aa3b, v8
	v_exp_f32_e32 v162, v162
	v_lshlrev_b32_e32 v164, 16, v131
	v_add_f32_e32 v162, 1.0, v162
	v_rcp_f32_e32 v162, v162
	s_nop 0
	v_mul_f32_e32 v8, v8, v162
	v_cvt_pk_bf16_f32 v8, v8, s0
	ds_write_b16 v71, v8 offset:5440
	v_mul_f32_e32 v8, v6, v9
	v_fmac_f32_e32 v8, v1, v117
	v_fmac_f32_e32 v8, v111, v115
	v_lshlrev_b32_e32 v117, 16, v137
	v_fmac_f32_e32 v8, v113, v117
	v_mul_f32_e32 v137, 0xbfb8aa3b, v8
	v_exp_f32_e32 v137, v137
	v_pk_mov_b32 v[162:163], v[160:161], v[174:175] op_sel:[1,0]
	v_add_f32_e32 v137, 1.0, v137
	v_rcp_f32_e32 v137, v137
	s_nop 0
	v_mul_f32_e32 v8, v8, v137
	v_cvt_pk_bf16_f32 v8, v8, s0
	ds_write_b16 v71, v8 offset:5712
	v_mul_f32_e32 v8, v6, v115
	v_fmac_f32_e32 v8, v1, v9
	v_fmac_f32_e32 v8, v111, v117
	v_lshlrev_b32_e32 v9, 16, v127
	v_fmac_f32_e32 v8, v113, v9
	v_mul_f32_e32 v127, 0xbfb8aa3b, v8
	v_exp_f32_e32 v127, v127
	s_nop 0
	v_add_f32_e32 v127, 1.0, v127
	v_rcp_f32_e32 v127, v127
	s_nop 0
	v_mul_f32_e32 v8, v8, v127
	v_cvt_pk_bf16_f32 v8, v8, s0
	ds_write_b16 v71, v8 offset:5984
	v_mul_f32_e32 v8, v6, v117
	v_fmac_f32_e32 v8, v1, v115
	v_fmac_f32_e32 v8, v111, v9
	v_lshlrev_b32_e32 v115, 16, v121
	v_fmac_f32_e32 v8, v113, v115
	v_mul_f32_e32 v121, 0xbfb8aa3b, v8
	v_exp_f32_e32 v121, v121
	s_nop 0
	v_add_f32_e32 v121, 1.0, v121
	v_rcp_f32_e32 v121, v121
	s_nop 0
	v_mul_f32_e32 v8, v8, v121
	v_cvt_pk_bf16_f32 v8, v8, s0
	ds_write_b16 v71, v8 offset:6256
	v_mul_f32_e32 v8, v6, v9
	v_fmac_f32_e32 v8, v1, v117
	v_fmac_f32_e32 v8, v111, v115
	v_lshlrev_b32_e32 v117, 16, v119
	v_fmac_f32_e32 v8, v113, v117
	v_mul_f32_e32 v119, 0xbfb8aa3b, v8
	v_exp_f32_e32 v119, v119
	s_nop 0
	v_add_f32_e32 v119, 1.0, v119
	v_rcp_f32_e32 v119, v119
	s_nop 0
	v_mul_f32_e32 v8, v8, v119
	v_cvt_pk_bf16_f32 v8, v8, s0
	ds_write_b16 v71, v8 offset:6528
	v_mul_f32_e32 v8, v6, v115
	v_fmac_f32_e32 v8, v1, v9
	v_fmac_f32_e32 v8, v111, v117
	v_lshlrev_b32_e32 v9, 16, v21
	v_fmac_f32_e32 v8, v113, v9
	v_mul_f32_e32 v21, 0xbfb8aa3b, v8
	v_exp_f32_e32 v21, v21
	s_nop 0
	v_add_f32_e32 v21, 1.0, v21
	v_rcp_f32_e32 v21, v21
	s_nop 0
	v_mul_f32_e32 v8, v8, v21
	v_cvt_pk_bf16_f32 v8, v8, s0
	ds_write_b16 v71, v8 offset:6800
	v_mul_f32_e32 v8, v6, v117
	v_fmac_f32_e32 v8, v1, v115
	v_fmac_f32_e32 v8, v111, v9
	v_fmac_f32_e32 v8, v113, v20
	v_mul_f32_e32 v21, 0xbfb8aa3b, v8
	v_exp_f32_e32 v21, v21
	s_nop 0
	v_add_f32_e32 v21, 1.0, v21
	v_rcp_f32_e32 v21, v21
	s_nop 0
	v_mul_f32_e32 v8, v8, v21
	v_cvt_pk_bf16_f32 v8, v8, s0
	ds_write_b16 v71, v8 offset:7072
	v_mul_f32_e32 v8, v6, v9
	v_fmac_f32_e32 v8, v1, v117
	v_fmac_f32_e32 v8, v111, v20
	v_fmac_f32_e32 v8, v113, v17
	v_mul_f32_e32 v21, 0xbfb8aa3b, v8
	v_exp_f32_e32 v21, v21
	s_nop 0
	v_add_f32_e32 v21, 1.0, v21
	v_rcp_f32_e32 v21, v21
	s_nop 0
	v_mul_f32_e32 v8, v8, v21
	v_cvt_pk_bf16_f32 v8, v8, s0
	ds_write_b16 v71, v8 offset:7344
	v_mul_f32_e32 v8, v6, v20
	v_fmac_f32_e32 v8, v1, v9
	v_fmac_f32_e32 v8, v111, v17
	v_lshlrev_b32_e32 v9, 16, v16
	v_fmac_f32_e32 v8, v113, v9
	v_mul_f32_e32 v16, 0xbfb8aa3b, v8
	v_exp_f32_e32 v16, v16
	s_nop 0
	v_add_f32_e32 v16, 1.0, v16
	v_rcp_f32_e32 v16, v16
	s_nop 0
	v_mul_f32_e32 v8, v8, v16
	v_cvt_pk_bf16_f32 v8, v8, s0
	ds_write_b16 v71, v8 offset:7616
	v_mul_f32_e32 v8, v6, v17
	v_fmac_f32_e32 v8, v1, v20
	v_fmac_f32_e32 v8, v111, v9
	v_fmac_f32_e32 v8, v113, v14
	v_mul_f32_e32 v16, 0xbfb8aa3b, v8
	v_exp_f32_e32 v16, v16
	s_nop 0
	v_add_f32_e32 v16, 1.0, v16
	v_rcp_f32_e32 v16, v16
	s_nop 0
	v_mul_f32_e32 v8, v8, v16
	v_cvt_pk_bf16_f32 v8, v8, s0
	ds_write_b16 v71, v8 offset:7888
	v_mul_f32_e32 v8, v6, v9
	v_fmac_f32_e32 v8, v1, v17
	v_fmac_f32_e32 v8, v111, v14
	v_fmac_f32_e32 v8, v113, v12
	v_mul_f32_e32 v16, 0xbfb8aa3b, v8
	v_exp_f32_e32 v16, v16
	v_mul_f32_e32 v6, v6, v14
	v_fmac_f32_e32 v6, v1, v9
	v_lshlrev_b32_e32 v1, 16, v10
	v_add_f32_e32 v16, 1.0, v16
	v_rcp_f32_e32 v16, v16
	v_fmac_f32_e32 v6, v111, v12
	v_fmac_f32_e32 v6, v113, v1
	v_mul_f32_e32 v1, 0xbfb8aa3b, v6
	v_mul_f32_e32 v8, v8, v16
	v_lshl_add_u64 v[16:17], v[180:181], 2, s[78:79]
	v_add_co_u32_e32 v20, vcc, s1, v16
	v_cvt_pk_bf16_f32 v8, v8, s0
	s_nop 0
	v_addc_co_u32_e32 v21, vcc, 0, v17, vcc
	ds_write_b16 v71, v8 offset:8160
	global_load_dword v8, v[16:17], off
; DI float bf2f(bf16_t b) { return __uint_as_float(((unsigned)b) << 16); }
; DI float silu_fast(float x) { return x * __builtin_amdgcn_rcpf(1.f + __expf(-x)); }
; DI void gdn_prep_phase(const int tid, LAS unsigned char* lds, const P& p, int G, int c) {
;     ...
;             { const float w0 = convw[colkv], w1 = convw[2304 + colkv], w2 = convw[4608 + colkv], w3 = convw[6912 + colkv];
; #pragma unroll
;               for (int e = 0; e < 64; ++e) { const float y = w0 * bf2f(kvraw[e]) + w1 * bf2f(kvraw[e + 1]) + w2 * bf2f(kvraw[e + 2]) + w3 * bf2f(kvraw[e + 3]); xs[e] = silu_fast(y); }
	global_load_dword v10, v[20:21], off offset:1024
	v_add_co_u32_e32 v20, vcc, s26, v16
	v_exp_f32_e32 v1, v1
	s_nop 0
	v_addc_co_u32_e32 v21, vcc, 0, v17, vcc
	v_add_co_u32_e32 v16, vcc, s27, v16
	global_load_dword v12, v[20:21], off offset:2048
	s_nop 0
	v_addc_co_u32_e32 v17, vcc, 0, v17, vcc
	global_load_dword v14, v[16:17], off offset:3072
	v_add_f32_e32 v1, 1.0, v1
	v_rcp_f32_e32 v1, v1
	v_lshlrev_b32_e32 v9, 16, v22
	v_lshlrev_b32_e32 v22, 16, v24
	v_lshlrev_b32_e32 v24, 16, v26
	v_mul_f32_e32 v1, v6, v1
	v_mov_b32_e32 v6, v5
	v_cvt_pk_bf16_f32 v1, v1, s0
	ds_write_b16 v71, v1 offset:8432
	v_lshlrev_b32_e32 v26, 16, v28
	v_lshlrev_b32_e32 v28, 16, v30
	v_lshlrev_b32_e32 v30, 16, v32
	v_lshlrev_b32_e32 v32, 16, v34
	v_lshlrev_b32_e32 v34, 16, v36
	v_lshlrev_b32_e32 v36, 16, v38
	v_lshlrev_b32_e32 v38, 16, v40
	v_lshlrev_b32_e32 v40, 16, v42
	v_lshlrev_b32_e32 v42, 16, v44
	v_lshlrev_b32_e32 v44, 16, v46
	v_lshlrev_b32_e32 v46, 16, v48
	v_lshlrev_b32_e32 v48, 16, v50
	v_lshlrev_b32_e32 v50, 16, v52
	v_lshlrev_b32_e32 v52, 16, v54
	v_lshlrev_b32_e32 v54, 16, v56
	v_lshlrev_b32_e32 v56, 16, v58
	v_lshlrev_b32_e32 v58, 16, v60
	v_lshlrev_b32_e32 v60, 16, v62
	v_lshlrev_b32_e32 v62, 16, v64
	v_lshlrev_b32_e32 v64, 16, v66
	v_lshlrev_b32_e32 v66, 16, v123
	v_lshlrev_b32_e32 v16, 16, v13
	v_lshlrev_b32_e32 v17, 16, v15
	v_lshlrev_b32_e32 v21, 16, v18
	v_mov_b32_e32 v20, v17
	v_mov_b32_e32 v18, v21
	s_waitcnt vmcnt(2)
	v_pk_mul_f32 v[158:159], v[6:7], v[10:11] op_sel_hi:[1,0]
	s_nop 0
	v_pk_fma_f32 v[4:5], v[4:5], v[8:9], v[158:159] op_sel_hi:[1,0,1]
	v_mov_b32_e32 v158, v169
	v_mov_b32_e32 v159, v160
	v_mov_b32_e32 v11, v8
	v_mov_b32_e32 v6, v160
	v_pk_mul_f32 v[6:7], v[6:7], v[10:11]
	s_waitcnt vmcnt(1)
	v_pk_fma_f32 v[4:5], v[12:13], v[168:169], v[4:5] op_sel_hi:[0,1,1]
	s_waitcnt vmcnt(0)
	v_pk_fma_f32 v[4:5], v[14:15], v[158:159], v[4:5] op_sel_hi:[0,1,1]
	v_mul_f32_e32 v1, 0xbfb8aa3b, v4
	v_exp_f32_e32 v1, v1
	s_nop 0
	v_add_f32_e32 v1, 1.0, v1
	v_rcp_f32_e32 v158, v1
	v_mul_f32_e32 v1, 0xbfb8aa3b, v5
	v_exp_f32_e32 v1, v1
	s_nop 0
	v_add_f32_e32 v1, 1.0, v1
	v_rcp_f32_e32 v159, v1
	s_nop 0
	v_pk_mul_f32 v[158:159], v[4:5], v[158:159]
	v_mov_b32_e32 v4, v169
	v_pk_fma_f32 v[4:5], v[10:11], v[4:5], v[6:7] op_sel:[0,0,1] op_sel_hi:[1,0,0]
	s_nop 0
	v_pk_fma_f32 v[4:5], v[12:13], v[160:161], v[4:5] op_sel_hi:[0,1,1]
	v_pk_fma_f32 v[4:5], v[14:15], v[162:163], v[4:5] op_sel_hi:[0,1,1]
	v_mul_f32_e32 v1, 0xbfb8aa3b, v4
	v_exp_f32_e32 v1, v1
	s_nop 0
	v_add_f32_e32 v1, 1.0, v1
	v_rcp_f32_e32 v6, v1
	v_mul_f32_e32 v1, 0xbfb8aa3b, v5
	v_exp_f32_e32 v1, v1
	s_nop 0
	v_add_f32_e32 v1, 1.0, v1
	v_rcp_f32_e32 v7, v1
	s_nop 0
	v_pk_mul_f32 v[188:189], v[4:5], v[6:7]
	v_pk_mul_f32 v[6:7], v[10:11], v[162:163] op_sel_hi:[0,1]
	v_pk_fma_f32 v[6:7], v[8:9], v[160:161], v[6:7] op_sel_hi:[0,1,1]
	v_pk_mov_b32 v[4:5], v[174:175], v[172:173] op_sel:[1,0]
	v_pk_fma_f32 v[6:7], v[12:13], v[174:175], v[6:7] op_sel_hi:[0,1,1]
	v_pk_fma_f32 v[6:7], v[14:15], v[4:5], v[6:7] op_sel_hi:[0,1,1]
	v_mul_f32_e32 v1, 0xbfb8aa3b, v6
	v_exp_f32_e32 v1, v1
	v_pk_mul_f32 v[4:5], v[10:11], v[4:5] op_sel_hi:[0,1]
	v_pk_fma_f32 v[4:5], v[8:9], v[174:175], v[4:5] op_sel_hi:[0,1,1]
	v_pk_fma_f32 v[4:5], v[12:13], v[172:173], v[4:5] op_sel_hi:[0,1,1]
	v_add_f32_e32 v1, 1.0, v1
	v_rcp_f32_e32 v160, v1
	v_mul_f32_e32 v1, 0xbfb8aa3b, v7
	v_exp_f32_e32 v1, v1
	s_nop 0
	v_add_f32_e32 v1, 1.0, v1
	v_rcp_f32_e32 v161, v1
	s_nop 0
	v_pk_mul_f32 v[160:161], v[6:7], v[160:161]
	v_pk_mov_b32 v[6:7], v[172:173], v[170:171] op_sel:[1,0]
	s_nop 0
	v_pk_fma_f32 v[4:5], v[14:15], v[6:7], v[4:5] op_sel_hi:[0,1,1]
	v_mul_f32_e32 v1, 0xbfb8aa3b, v4
	v_exp_f32_e32 v1, v1
	v_pk_mul_f32 v[6:7], v[10:11], v[6:7] op_sel_hi:[0,1]
	v_pk_fma_f32 v[6:7], v[8:9], v[172:173], v[6:7] op_sel_hi:[0,1,1]
	v_pk_fma_f32 v[6:7], v[12:13], v[170:171], v[6:7] op_sel_hi:[0,1,1]
	v_add_f32_e32 v1, 1.0, v1
	v_rcp_f32_e32 v162, v1
	v_mul_f32_e32 v1, 0xbfb8aa3b, v5
	v_exp_f32_e32 v1, v1
	s_nop 0
	v_add_f32_e32 v1, 1.0, v1
	v_rcp_f32_e32 v163, v1
	s_nop 0
	v_pk_mul_f32 v[162:163], v[4:5], v[162:163]
	v_pk_mov_b32 v[4:5], v[170:171], v[164:165] op_sel:[1,0]
	s_nop 0
	v_pk_fma_f32 v[6:7], v[14:15], v[4:5], v[6:7] op_sel_hi:[0,1,1]
	v_mul_f32_e32 v1, 0xbfb8aa3b, v6
	v_exp_f32_e32 v1, v1
	v_pk_mul_f32 v[4:5], v[10:11], v[4:5] op_sel_hi:[0,1]
	v_pk_fma_f32 v[4:5], v[8:9], v[170:171], v[4:5] op_sel_hi:[0,1,1]
	v_pk_fma_f32 v[4:5], v[12:13], v[164:165], v[4:5] op_sel_hi:[0,1,1]
	v_add_f32_e32 v1, 1.0, v1
	v_rcp_f32_e32 v168, v1
	v_mul_f32_e32 v1, 0xbfb8aa3b, v7
	v_exp_f32_e32 v1, v1
	s_nop 0
	v_add_f32_e32 v1, 1.0, v1
	v_rcp_f32_e32 v169, v1
	s_nop 0
	v_pk_mul_f32 v[178:179], v[6:7], v[168:169]
	v_pk_mov_b32 v[6:7], v[164:165], v[166:167] op_sel:[1,0]
	s_nop 0
	v_pk_fma_f32 v[4:5], v[14:15], v[6:7], v[4:5] op_sel_hi:[0,1,1]
	v_mul_f32_e32 v1, 0xbfb8aa3b, v4
	v_exp_f32_e32 v1, v1
	v_pk_mul_f32 v[6:7], v[10:11], v[6:7] op_sel_hi:[0,1]
	v_pk_fma_f32 v[6:7], v[8:9], v[164:165], v[6:7] op_sel_hi:[0,1,1]
	v_pk_fma_f32 v[6:7], v[12:13], v[166:167], v[6:7] op_sel_hi:[0,1,1]
	v_add_f32_e32 v1, 1.0, v1
	v_rcp_f32_e32 v168, v1
	v_mul_f32_e32 v1, 0xbfb8aa3b, v5
	v_exp_f32_e32 v1, v1
	s_nop 0
	v_add_f32_e32 v1, 1.0, v1
	v_rcp_f32_e32 v169, v1
	s_nop 0
	v_pk_mul_f32 v[172:173], v[4:5], v[168:169]
	v_pk_mov_b32 v[4:5], v[166:167], v[66:67] op_sel:[1,0]
	s_nop 0
	v_pk_fma_f32 v[6:7], v[14:15], v[4:5], v[6:7] op_sel_hi:[0,1,1]
	v_mul_f32_e32 v1, 0xbfb8aa3b, v6
	v_exp_f32_e32 v1, v1
	v_pk_mul_f32 v[4:5], v[10:11], v[4:5] op_sel_hi:[0,1]
	v_pk_fma_f32 v[4:5], v[8:9], v[166:167], v[4:5] op_sel_hi:[0,1,1]
	v_pk_fma_f32 v[4:5], v[12:13], v[66:67], v[4:5] op_sel_hi:[0,1,1]
; DI float bf2f(bf16_t b) { return __uint_as_float(((unsigned)b) << 16); }
; DI float silu_fast(float x) { return x * __builtin_amdgcn_rcpf(1.f + __expf(-x)); }
; DI void gdn_prep_phase(const int tid, LAS unsigned char* lds, const P& p, int G, int c) {
;     ...
;             { const float w0 = convw[colkv], w1 = convw[2304 + colkv], w2 = convw[4608 + colkv], w3 = convw[6912 + colkv];
; #pragma unroll
;               for (int e = 0; e < 64; ++e) { const float y = w0 * bf2f(kvraw[e]) + w1 * bf2f(kvraw[e + 1]) + w2 * bf2f(kvraw[e + 2]) + w3 * bf2f(kvraw[e + 3]); xs[e] = silu_fast(y); }
	v_add_f32_e32 v1, 1.0, v1
	v_rcp_f32_e32 v164, v1
	v_mul_f32_e32 v1, 0xbfb8aa3b, v7
	v_exp_f32_e32 v1, v1
	s_nop 0
	v_add_f32_e32 v1, 1.0, v1
	v_rcp_f32_e32 v165, v1
	s_nop 0
	v_pk_mul_f32 v[164:165], v[6:7], v[164:165]
	v_pk_mov_b32 v[6:7], v[66:67], v[64:65] op_sel:[1,0]
	s_nop 0
	v_pk_fma_f32 v[4:5], v[14:15], v[6:7], v[4:5] op_sel_hi:[0,1,1]
	v_mul_f32_e32 v1, 0xbfb8aa3b, v4
	v_exp_f32_e32 v1, v1
	v_pk_mul_f32 v[6:7], v[10:11], v[6:7] op_sel_hi:[0,1]
	v_pk_fma_f32 v[6:7], v[8:9], v[66:67], v[6:7] op_sel_hi:[0,1,1]
	v_pk_fma_f32 v[6:7], v[12:13], v[64:65], v[6:7] op_sel_hi:[0,1,1]
	v_add_f32_e32 v1, 1.0, v1
	v_rcp_f32_e32 v166, v1
	v_mul_f32_e32 v1, 0xbfb8aa3b, v5
	v_exp_f32_e32 v1, v1
	s_nop 0
	v_add_f32_e32 v1, 1.0, v1
	v_rcp_f32_e32 v167, v1
	s_nop 0
	v_pk_mul_f32 v[166:167], v[4:5], v[166:167]
	v_pk_mov_b32 v[4:5], v[64:65], v[62:63] op_sel:[1,0]
	s_nop 0
	v_pk_fma_f32 v[6:7], v[14:15], v[4:5], v[6:7] op_sel_hi:[0,1,1]
	v_mul_f32_e32 v1, 0xbfb8aa3b, v6
	v_exp_f32_e32 v1, v1
	v_pk_mul_f32 v[4:5], v[10:11], v[4:5] op_sel_hi:[0,1]
	v_pk_fma_f32 v[4:5], v[8:9], v[64:65], v[4:5] op_sel_hi:[0,1,1]
	v_pk_fma_f32 v[4:5], v[12:13], v[62:63], v[4:5] op_sel_hi:[0,1,1]
	v_add_f32_e32 v1, 1.0, v1
	v_rcp_f32_e32 v66, v1
	v_mul_f32_e32 v1, 0xbfb8aa3b, v7
	v_exp_f32_e32 v1, v1
	s_nop 0
	v_add_f32_e32 v1, 1.0, v1
	v_rcp_f32_e32 v67, v1
	s_nop 0
	v_pk_mul_f32 v[168:169], v[6:7], v[66:67]
	v_pk_mov_b32 v[6:7], v[62:63], v[60:61] op_sel:[1,0]
	s_nop 0
	v_pk_fma_f32 v[4:5], v[14:15], v[6:7], v[4:5] op_sel_hi:[0,1,1]
	v_mul_f32_e32 v1, 0xbfb8aa3b, v4
	v_exp_f32_e32 v1, v1
	v_pk_mul_f32 v[6:7], v[10:11], v[6:7] op_sel_hi:[0,1]
	v_pk_fma_f32 v[6:7], v[8:9], v[62:63], v[6:7] op_sel_hi:[0,1,1]
	v_pk_fma_f32 v[6:7], v[12:13], v[60:61], v[6:7] op_sel_hi:[0,1,1]
	v_add_f32_e32 v1, 1.0, v1
	v_rcp_f32_e32 v64, v1
	v_mul_f32_e32 v1, 0xbfb8aa3b, v5
	v_exp_f32_e32 v1, v1
	s_nop 0
	v_add_f32_e32 v1, 1.0, v1
	v_rcp_f32_e32 v65, v1
	s_nop 0
	v_pk_mul_f32 v[170:171], v[4:5], v[64:65]
	v_pk_mov_b32 v[4:5], v[60:61], v[58:59] op_sel:[1,0]
	s_nop 0
	v_pk_fma_f32 v[6:7], v[14:15], v[4:5], v[6:7] op_sel_hi:[0,1,1]
	v_mul_f32_e32 v1, 0xbfb8aa3b, v6
	v_exp_f32_e32 v1, v1
	v_pk_mul_f32 v[4:5], v[10:11], v[4:5] op_sel_hi:[0,1]
	v_pk_fma_f32 v[4:5], v[8:9], v[60:61], v[4:5] op_sel_hi:[0,1,1]
	v_pk_fma_f32 v[4:5], v[12:13], v[58:59], v[4:5] op_sel_hi:[0,1,1]
	v_add_f32_e32 v1, 1.0, v1
	v_rcp_f32_e32 v62, v1
	v_mul_f32_e32 v1, 0xbfb8aa3b, v7
	v_exp_f32_e32 v1, v1
	s_nop 0
	v_add_f32_e32 v1, 1.0, v1
	v_rcp_f32_e32 v63, v1
	s_nop 0
	v_pk_mul_f32 v[174:175], v[6:7], v[62:63]
	v_pk_mov_b32 v[6:7], v[58:59], v[56:57] op_sel:[1,0]
	s_nop 0
	v_pk_fma_f32 v[4:5], v[14:15], v[6:7], v[4:5] op_sel_hi:[0,1,1]
	v_mul_f32_e32 v1, 0xbfb8aa3b, v4
	v_exp_f32_e32 v1, v1
	v_pk_mul_f32 v[6:7], v[10:11], v[6:7] op_sel_hi:[0,1]
	v_pk_fma_f32 v[6:7], v[8:9], v[58:59], v[6:7] op_sel_hi:[0,1,1]
	v_pk_fma_f32 v[6:7], v[12:13], v[56:57], v[6:7] op_sel_hi:[0,1,1]
	v_add_f32_e32 v1, 1.0, v1
	v_rcp_f32_e32 v60, v1
	v_mul_f32_e32 v1, 0xbfb8aa3b, v5
	v_exp_f32_e32 v1, v1
	s_nop 0
	v_add_f32_e32 v1, 1.0, v1
	v_rcp_f32_e32 v61, v1
	s_nop 0
	v_pk_mul_f32 v[176:177], v[4:5], v[60:61]
	v_pk_mov_b32 v[4:5], v[56:57], v[54:55] op_sel:[1,0]
	s_nop 0
	v_pk_fma_f32 v[6:7], v[14:15], v[4:5], v[6:7] op_sel_hi:[0,1,1]
	v_mul_f32_e32 v1, 0xbfb8aa3b, v6
	v_exp_f32_e32 v1, v1
	v_pk_mul_f32 v[4:5], v[10:11], v[4:5] op_sel_hi:[0,1]
	v_pk_fma_f32 v[4:5], v[8:9], v[56:57], v[4:5] op_sel_hi:[0,1,1]
	v_pk_fma_f32 v[4:5], v[12:13], v[54:55], v[4:5] op_sel_hi:[0,1,1]
	v_add_f32_e32 v1, 1.0, v1
	v_rcp_f32_e32 v58, v1
	v_mul_f32_e32 v1, 0xbfb8aa3b, v7
	v_exp_f32_e32 v1, v1
	s_nop 0
	v_add_f32_e32 v1, 1.0, v1
	v_rcp_f32_e32 v59, v1
	s_nop 0
	v_pk_mul_f32 v[184:185], v[6:7], v[58:59]
	v_pk_mov_b32 v[6:7], v[54:55], v[52:53] op_sel:[1,0]
	s_nop 0
	v_pk_fma_f32 v[4:5], v[14:15], v[6:7], v[4:5] op_sel_hi:[0,1,1]
	v_mul_f32_e32 v1, 0xbfb8aa3b, v4
	v_exp_f32_e32 v1, v1
	v_pk_mul_f32 v[6:7], v[10:11], v[6:7] op_sel_hi:[0,1]
	v_pk_fma_f32 v[6:7], v[8:9], v[54:55], v[6:7] op_sel_hi:[0,1,1]
	v_pk_fma_f32 v[6:7], v[12:13], v[52:53], v[6:7] op_sel_hi:[0,1,1]
	v_add_f32_e32 v1, 1.0, v1
	v_rcp_f32_e32 v56, v1
	v_mul_f32_e32 v1, 0xbfb8aa3b, v5
	v_exp_f32_e32 v1, v1
	s_nop 0
	v_add_f32_e32 v1, 1.0, v1
	v_rcp_f32_e32 v57, v1
	s_nop 0
	v_pk_mul_f32 v[186:187], v[4:5], v[56:57]
	v_pk_mov_b32 v[4:5], v[52:53], v[50:51] op_sel:[1,0]
	s_nop 0
	v_pk_fma_f32 v[6:7], v[14:15], v[4:5], v[6:7] op_sel_hi:[0,1,1]
	v_mul_f32_e32 v1, 0xbfb8aa3b, v6
	v_exp_f32_e32 v1, v1
	v_pk_mul_f32 v[4:5], v[10:11], v[4:5] op_sel_hi:[0,1]
	v_pk_fma_f32 v[4:5], v[8:9], v[52:53], v[4:5] op_sel_hi:[0,1,1]
	v_pk_fma_f32 v[4:5], v[12:13], v[50:51], v[4:5] op_sel_hi:[0,1,1]
	v_add_f32_e32 v1, 1.0, v1
	v_rcp_f32_e32 v54, v1
	v_mul_f32_e32 v1, 0xbfb8aa3b, v7
	v_exp_f32_e32 v1, v1
	s_nop 0
	v_add_f32_e32 v1, 1.0, v1
	v_rcp_f32_e32 v55, v1
	s_nop 0
	v_pk_mul_f32 v[190:191], v[6:7], v[54:55]
	v_pk_mov_b32 v[6:7], v[50:51], v[48:49] op_sel:[1,0]
	s_nop 0
	v_pk_fma_f32 v[4:5], v[14:15], v[6:7], v[4:5] op_sel_hi:[0,1,1]
	v_mul_f32_e32 v1, 0xbfb8aa3b, v4
	v_exp_f32_e32 v1, v1
	v_pk_mul_f32 v[6:7], v[10:11], v[6:7] op_sel_hi:[0,1]
	v_pk_fma_f32 v[6:7], v[8:9], v[50:51], v[6:7] op_sel_hi:[0,1,1]
	v_pk_fma_f32 v[6:7], v[12:13], v[48:49], v[6:7] op_sel_hi:[0,1,1]
	v_add_f32_e32 v1, 1.0, v1
	v_rcp_f32_e32 v52, v1
	v_mul_f32_e32 v1, 0xbfb8aa3b, v5
	v_exp_f32_e32 v1, v1
	s_nop 0
	v_add_f32_e32 v1, 1.0, v1
	v_rcp_f32_e32 v53, v1
	s_nop 0
	v_pk_mul_f32 v[192:193], v[4:5], v[52:53]
	v_pk_mov_b32 v[4:5], v[48:49], v[46:47] op_sel:[1,0]
	s_nop 0
	v_pk_fma_f32 v[6:7], v[14:15], v[4:5], v[6:7] op_sel_hi:[0,1,1]
; DI float bf2f(bf16_t b) { return __uint_as_float(((unsigned)b) << 16); }
; DI float silu_fast(float x) { return x * __builtin_amdgcn_rcpf(1.f + __expf(-x)); }
; DI void gdn_prep_phase(const int tid, LAS unsigned char* lds, const P& p, int G, int c) {
;     ...
;             { const float w0 = convw[colkv], w1 = convw[2304 + colkv], w2 = convw[4608 + colkv], w3 = convw[6912 + colkv];
; #pragma unroll
;               for (int e = 0; e < 64; ++e) { const float y = w0 * bf2f(kvraw[e]) + w1 * bf2f(kvraw[e + 1]) + w2 * bf2f(kvraw[e + 2]) + w3 * bf2f(kvraw[e + 3]); xs[e] = silu_fast(y); }
	v_mul_f32_e32 v1, 0xbfb8aa3b, v6
	v_exp_f32_e32 v1, v1
	v_pk_mul_f32 v[4:5], v[10:11], v[4:5] op_sel_hi:[0,1]
	v_pk_fma_f32 v[4:5], v[8:9], v[48:49], v[4:5] op_sel_hi:[0,1,1]
	v_pk_fma_f32 v[4:5], v[12:13], v[46:47], v[4:5] op_sel_hi:[0,1,1]
	v_add_f32_e32 v1, 1.0, v1
	v_rcp_f32_e32 v50, v1
	v_mul_f32_e32 v1, 0xbfb8aa3b, v7
	v_exp_f32_e32 v1, v1
	s_nop 0
	v_add_f32_e32 v1, 1.0, v1
	v_rcp_f32_e32 v51, v1
	s_nop 0
	v_pk_mul_f32 v[194:195], v[6:7], v[50:51]
	v_pk_mov_b32 v[6:7], v[46:47], v[44:45] op_sel:[1,0]
	s_nop 0
	v_pk_fma_f32 v[4:5], v[14:15], v[6:7], v[4:5] op_sel_hi:[0,1,1]
	v_mul_f32_e32 v1, 0xbfb8aa3b, v4
	v_exp_f32_e32 v1, v1
	v_pk_mul_f32 v[6:7], v[10:11], v[6:7] op_sel_hi:[0,1]
	v_pk_fma_f32 v[6:7], v[8:9], v[46:47], v[6:7] op_sel_hi:[0,1,1]
	v_pk_fma_f32 v[6:7], v[12:13], v[44:45], v[6:7] op_sel_hi:[0,1,1]
	v_add_f32_e32 v1, 1.0, v1
	v_rcp_f32_e32 v48, v1
	v_mul_f32_e32 v1, 0xbfb8aa3b, v5
	v_exp_f32_e32 v1, v1
	s_nop 0
	v_add_f32_e32 v1, 1.0, v1
	v_rcp_f32_e32 v49, v1
	s_nop 0
	v_pk_mul_f32 v[196:197], v[4:5], v[48:49]
	v_pk_mov_b32 v[4:5], v[44:45], v[42:43] op_sel:[1,0]
	s_nop 0
	v_pk_fma_f32 v[6:7], v[14:15], v[4:5], v[6:7] op_sel_hi:[0,1,1]
	v_mul_f32_e32 v1, 0xbfb8aa3b, v6
	v_exp_f32_e32 v1, v1
	v_pk_mul_f32 v[4:5], v[10:11], v[4:5] op_sel_hi:[0,1]
	v_pk_fma_f32 v[4:5], v[8:9], v[44:45], v[4:5] op_sel_hi:[0,1,1]
	v_pk_fma_f32 v[4:5], v[12:13], v[42:43], v[4:5] op_sel_hi:[0,1,1]
	v_add_f32_e32 v1, 1.0, v1
	v_rcp_f32_e32 v46, v1
	v_mul_f32_e32 v1, 0xbfb8aa3b, v7
	v_exp_f32_e32 v1, v1
	s_nop 0
	v_add_f32_e32 v1, 1.0, v1
	v_rcp_f32_e32 v47, v1
	s_nop 0
	v_pk_mul_f32 v[198:199], v[6:7], v[46:47]
	v_pk_mov_b32 v[6:7], v[42:43], v[40:41] op_sel:[1,0]
	s_nop 0
	v_pk_fma_f32 v[4:5], v[14:15], v[6:7], v[4:5] op_sel_hi:[0,1,1]
	v_mul_f32_e32 v1, 0xbfb8aa3b, v4
	v_exp_f32_e32 v1, v1
	v_pk_mul_f32 v[6:7], v[10:11], v[6:7] op_sel_hi:[0,1]
	v_pk_fma_f32 v[6:7], v[8:9], v[42:43], v[6:7] op_sel_hi:[0,1,1]
	v_pk_fma_f32 v[6:7], v[12:13], v[40:41], v[6:7] op_sel_hi:[0,1,1]
	v_add_f32_e32 v1, 1.0, v1
	v_rcp_f32_e32 v44, v1
	v_mul_f32_e32 v1, 0xbfb8aa3b, v5
	v_exp_f32_e32 v1, v1
	s_nop 0
	v_add_f32_e32 v1, 1.0, v1
	v_rcp_f32_e32 v45, v1
	s_nop 0
	v_pk_mul_f32 v[200:201], v[4:5], v[44:45]
	v_pk_mov_b32 v[4:5], v[40:41], v[38:39] op_sel:[1,0]
	s_nop 0
	v_pk_fma_f32 v[6:7], v[14:15], v[4:5], v[6:7] op_sel_hi:[0,1,1]
	v_mul_f32_e32 v1, 0xbfb8aa3b, v6
	v_exp_f32_e32 v1, v1
	v_pk_mul_f32 v[4:5], v[10:11], v[4:5] op_sel_hi:[0,1]
	v_pk_fma_f32 v[4:5], v[8:9], v[40:41], v[4:5] op_sel_hi:[0,1,1]
	v_pk_fma_f32 v[4:5], v[12:13], v[38:39], v[4:5] op_sel_hi:[0,1,1]
	v_add_f32_e32 v1, 1.0, v1
	v_rcp_f32_e32 v42, v1
	v_mul_f32_e32 v1, 0xbfb8aa3b, v7
	v_exp_f32_e32 v1, v1
	s_nop 0
	v_add_f32_e32 v1, 1.0, v1
	v_rcp_f32_e32 v43, v1
	s_nop 0
	v_pk_mul_f32 v[202:203], v[6:7], v[42:43]
	v_pk_mov_b32 v[6:7], v[38:39], v[36:37] op_sel:[1,0]
	s_nop 0
	v_pk_fma_f32 v[4:5], v[14:15], v[6:7], v[4:5] op_sel_hi:[0,1,1]
	v_mul_f32_e32 v1, 0xbfb8aa3b, v4
	v_exp_f32_e32 v1, v1
	v_pk_mul_f32 v[6:7], v[10:11], v[6:7] op_sel_hi:[0,1]
	v_pk_fma_f32 v[6:7], v[8:9], v[38:39], v[6:7] op_sel_hi:[0,1,1]
	v_pk_fma_f32 v[6:7], v[12:13], v[36:37], v[6:7] op_sel_hi:[0,1,1]
	v_add_f32_e32 v1, 1.0, v1
	v_rcp_f32_e32 v40, v1
	v_mul_f32_e32 v1, 0xbfb8aa3b, v5
	v_exp_f32_e32 v1, v1
	s_nop 0
	v_add_f32_e32 v1, 1.0, v1
	v_rcp_f32_e32 v41, v1
	s_nop 0
	v_pk_mul_f32 v[204:205], v[4:5], v[40:41]
	v_pk_mov_b32 v[4:5], v[36:37], v[34:35] op_sel:[1,0]
	s_nop 0
	v_pk_fma_f32 v[6:7], v[14:15], v[4:5], v[6:7] op_sel_hi:[0,1,1]
	v_mul_f32_e32 v1, 0xbfb8aa3b, v6
	v_exp_f32_e32 v1, v1
	v_pk_mul_f32 v[4:5], v[10:11], v[4:5] op_sel_hi:[0,1]
	v_pk_fma_f32 v[4:5], v[8:9], v[36:37], v[4:5] op_sel_hi:[0,1,1]
	v_pk_fma_f32 v[4:5], v[12:13], v[34:35], v[4:5] op_sel_hi:[0,1,1]
	v_add_f32_e32 v1, 1.0, v1
	v_rcp_f32_e32 v38, v1
	v_mul_f32_e32 v1, 0xbfb8aa3b, v7
	v_exp_f32_e32 v1, v1
	s_nop 0
	v_add_f32_e32 v1, 1.0, v1
	v_rcp_f32_e32 v39, v1
	s_nop 0
	v_pk_mul_f32 v[206:207], v[6:7], v[38:39]
	v_pk_mov_b32 v[6:7], v[34:35], v[32:33] op_sel:[1,0]
	s_nop 0
	v_pk_fma_f32 v[4:5], v[14:15], v[6:7], v[4:5] op_sel_hi:[0,1,1]
	v_mul_f32_e32 v1, 0xbfb8aa3b, v4
	v_exp_f32_e32 v1, v1
	v_pk_mul_f32 v[6:7], v[10:11], v[6:7] op_sel_hi:[0,1]
	v_pk_fma_f32 v[6:7], v[8:9], v[34:35], v[6:7] op_sel_hi:[0,1,1]
	v_pk_fma_f32 v[6:7], v[12:13], v[32:33], v[6:7] op_sel_hi:[0,1,1]
	v_add_f32_e32 v1, 1.0, v1
	v_rcp_f32_e32 v36, v1
	v_mul_f32_e32 v1, 0xbfb8aa3b, v5
	v_exp_f32_e32 v1, v1
	s_nop 0
	v_add_f32_e32 v1, 1.0, v1
	v_rcp_f32_e32 v37, v1
	s_nop 0
	v_pk_mul_f32 v[208:209], v[4:5], v[36:37]
	v_pk_mov_b32 v[4:5], v[32:33], v[30:31] op_sel:[1,0]
	s_nop 0
	v_pk_fma_f32 v[6:7], v[14:15], v[4:5], v[6:7] op_sel_hi:[0,1,1]
	v_mul_f32_e32 v1, 0xbfb8aa3b, v6
	v_exp_f32_e32 v1, v1
	v_pk_mul_f32 v[4:5], v[10:11], v[4:5] op_sel_hi:[0,1]
	v_pk_fma_f32 v[4:5], v[8:9], v[32:33], v[4:5] op_sel_hi:[0,1,1]
	v_pk_fma_f32 v[4:5], v[12:13], v[30:31], v[4:5] op_sel_hi:[0,1,1]
	v_add_f32_e32 v1, 1.0, v1
	v_rcp_f32_e32 v34, v1
	v_mul_f32_e32 v1, 0xbfb8aa3b, v7
	v_exp_f32_e32 v1, v1
	s_nop 0
	v_add_f32_e32 v1, 1.0, v1
	v_rcp_f32_e32 v35, v1
	s_nop 0
	v_pk_mul_f32 v[210:211], v[6:7], v[34:35]
	v_pk_mov_b32 v[6:7], v[30:31], v[28:29] op_sel:[1,0]
	s_nop 0
	v_pk_fma_f32 v[4:5], v[14:15], v[6:7], v[4:5] op_sel_hi:[0,1,1]
	v_mul_f32_e32 v1, 0xbfb8aa3b, v4
	v_exp_f32_e32 v1, v1
	v_pk_mul_f32 v[6:7], v[10:11], v[6:7] op_sel_hi:[0,1]
	v_pk_fma_f32 v[6:7], v[8:9], v[30:31], v[6:7] op_sel_hi:[0,1,1]
	v_pk_fma_f32 v[6:7], v[12:13], v[28:29], v[6:7] op_sel_hi:[0,1,1]
	v_add_f32_e32 v1, 1.0, v1
	v_rcp_f32_e32 v32, v1
	v_mul_f32_e32 v1, 0xbfb8aa3b, v5
	v_exp_f32_e32 v1, v1
; DI float bf2f(bf16_t b) { return __uint_as_float(((unsigned)b) << 16); }
; DI float silu_fast(float x) { return x * __builtin_amdgcn_rcpf(1.f + __expf(-x)); }
; DI void gdn_prep_phase(const int tid, LAS unsigned char* lds, const P& p, int G, int c) {
;     ...
;             { const float w0 = convw[colkv], w1 = convw[2304 + colkv], w2 = convw[4608 + colkv], w3 = convw[6912 + colkv];
; #pragma unroll
;               for (int e = 0; e < 64; ++e) { const float y = w0 * bf2f(kvraw[e]) + w1 * bf2f(kvraw[e + 1]) + w2 * bf2f(kvraw[e + 2]) + w3 * bf2f(kvraw[e + 3]); xs[e] = silu_fast(y); }
;               if (!isv) {
	s_nop 0
	v_add_f32_e32 v1, 1.0, v1
	v_rcp_f32_e32 v33, v1
	s_nop 0
	v_pk_mul_f32 v[212:213], v[4:5], v[32:33]
	v_pk_mov_b32 v[4:5], v[28:29], v[26:27] op_sel:[1,0]
	s_nop 0
	v_pk_fma_f32 v[6:7], v[14:15], v[4:5], v[6:7] op_sel_hi:[0,1,1]
	v_mul_f32_e32 v1, 0xbfb8aa3b, v6
	v_exp_f32_e32 v1, v1
	v_pk_mul_f32 v[4:5], v[10:11], v[4:5] op_sel_hi:[0,1]
	v_pk_fma_f32 v[4:5], v[8:9], v[28:29], v[4:5] op_sel_hi:[0,1,1]
	v_pk_fma_f32 v[4:5], v[12:13], v[26:27], v[4:5] op_sel_hi:[0,1,1]
	v_add_f32_e32 v1, 1.0, v1
	v_rcp_f32_e32 v30, v1
	v_mul_f32_e32 v1, 0xbfb8aa3b, v7
	v_exp_f32_e32 v1, v1
	s_nop 0
	v_add_f32_e32 v1, 1.0, v1
	v_rcp_f32_e32 v31, v1
	s_nop 0
	v_pk_mul_f32 v[214:215], v[6:7], v[30:31]
	v_pk_mov_b32 v[6:7], v[26:27], v[24:25] op_sel:[1,0]
	s_nop 0
	v_pk_fma_f32 v[4:5], v[14:15], v[6:7], v[4:5] op_sel_hi:[0,1,1]
	v_mul_f32_e32 v1, 0xbfb8aa3b, v4
	v_exp_f32_e32 v1, v1
	v_pk_mul_f32 v[6:7], v[10:11], v[6:7] op_sel_hi:[0,1]
	v_pk_fma_f32 v[6:7], v[8:9], v[26:27], v[6:7] op_sel_hi:[0,1,1]
	v_pk_fma_f32 v[6:7], v[12:13], v[24:25], v[6:7] op_sel_hi:[0,1,1]
	v_add_f32_e32 v1, 1.0, v1
	v_rcp_f32_e32 v28, v1
	v_mul_f32_e32 v1, 0xbfb8aa3b, v5
	v_exp_f32_e32 v1, v1
	s_nop 0
	v_add_f32_e32 v1, 1.0, v1
	v_rcp_f32_e32 v29, v1
	s_nop 0
	v_pk_mul_f32 v[216:217], v[4:5], v[28:29]
	v_pk_mov_b32 v[4:5], v[24:25], v[22:23] op_sel:[1,0]
	s_nop 0
	v_pk_fma_f32 v[6:7], v[14:15], v[4:5], v[6:7] op_sel_hi:[0,1,1]
	v_mul_f32_e32 v1, 0xbfb8aa3b, v6
	v_exp_f32_e32 v1, v1
	v_pk_mul_f32 v[4:5], v[10:11], v[4:5] op_sel_hi:[0,1]
	v_pk_fma_f32 v[4:5], v[8:9], v[24:25], v[4:5] op_sel_hi:[0,1,1]
	v_pk_fma_f32 v[4:5], v[12:13], v[22:23], v[4:5] op_sel_hi:[0,1,1]
	v_add_f32_e32 v1, 1.0, v1
	v_rcp_f32_e32 v26, v1
	v_mul_f32_e32 v1, 0xbfb8aa3b, v7
	v_exp_f32_e32 v1, v1
	s_nop 0
	v_add_f32_e32 v1, 1.0, v1
	v_rcp_f32_e32 v27, v1
	s_nop 0
	v_pk_mul_f32 v[218:219], v[6:7], v[26:27]
	v_pk_mov_b32 v[6:7], v[22:23], v[16:17] op_sel:[1,0]
	s_nop 0
	v_pk_fma_f32 v[4:5], v[14:15], v[6:7], v[4:5] op_sel_hi:[0,1,1]
	v_mul_f32_e32 v1, 0xbfb8aa3b, v4
	v_exp_f32_e32 v1, v1
	s_nop 0
	v_add_f32_e32 v1, 1.0, v1
	v_rcp_f32_e32 v24, v1
	v_mul_f32_e32 v1, 0xbfb8aa3b, v5
	v_exp_f32_e32 v1, v1
	s_nop 0
	v_add_f32_e32 v1, 1.0, v1
	v_rcp_f32_e32 v25, v1
	s_nop 0
	v_pk_mul_f32 v[220:221], v[4:5], v[24:25]
	v_pk_mul_f32 v[4:5], v[10:11], v[6:7] op_sel_hi:[0,1]
	v_pk_fma_f32 v[4:5], v[8:9], v[22:23], v[4:5] op_sel_hi:[0,1,1]
	v_pk_fma_f32 v[4:5], v[12:13], v[16:17], v[4:5] op_sel_hi:[0,1,1]
	v_pk_fma_f32 v[4:5], v[14:15], v[20:21], v[4:5] op_sel_hi:[0,1,1]
	v_mul_f32_e32 v1, 0xbfb8aa3b, v4
	v_exp_f32_e32 v1, v1
	s_nop 0
	v_add_f32_e32 v1, 1.0, v1
	v_rcp_f32_e32 v6, v1
	v_mul_f32_e32 v1, 0xbfb8aa3b, v5
	v_exp_f32_e32 v1, v1
	s_nop 0
	v_add_f32_e32 v1, 1.0, v1
	v_rcp_f32_e32 v7, v1
	s_nop 0
	v_pk_mul_f32 v[222:223], v[4:5], v[6:7]
	v_pk_mul_f32 v[4:5], v[10:11], v[20:21] op_sel_hi:[0,1]
	v_pk_fma_f32 v[4:5], v[8:9], v[16:17], v[4:5] op_sel_hi:[0,1,1]
	v_mov_b32_e32 v8, v19
	v_pk_fma_f32 v[4:5], v[12:13], v[18:19], v[4:5] op_sel_hi:[0,1,1]
	v_pk_fma_f32 v[4:5], v[14:15], v[8:9], v[4:5] op_sel_hi:[0,1,1]
	v_mul_f32_e32 v1, 0xbfb8aa3b, v4
	v_exp_f32_e32 v1, v1
	s_nop 0
	v_add_f32_e32 v1, 1.0, v1
	v_rcp_f32_e32 v6, v1
	v_mul_f32_e32 v1, 0xbfb8aa3b, v5
	v_exp_f32_e32 v1, v1
	s_nop 0
	v_add_f32_e32 v1, 1.0, v1
	v_rcp_f32_e32 v7, v1
	s_nop 0
	v_pk_mul_f32 v[224:225], v[4:5], v[6:7]
	s_mov_b64 s[0:1], exec
	v_readlane_b32 s26, v254, 54
	v_readlane_b32 s27, v254, 55
	s_and_b64 s[26:27], s[0:1], s[26:27]
	s_mov_b64 exec, s[26:27]
	s_cbranch_execz .LBB0_608
; DI void gdn_prep_phase(const int tid, LAS unsigned char* lds, const P& p, int G, int c) {
;     ...
;               if (!isv) {
; #pragma unroll
;                   for (int tt = 0; tt < 64; ++tt) Ks[tt * 136 + ch] = f2bf(xs[tt]); } }
	v_cvt_pk_bf16_f32 v1, v158, s0
	ds_write_b16 v75, v1 offset:17408
	v_cvt_pk_bf16_f32 v1, v159, s0
	ds_write_b16 v75, v1 offset:17680
	v_cvt_pk_bf16_f32 v1, v188, s0
	ds_write_b16 v75, v1 offset:17952
	v_cvt_pk_bf16_f32 v1, v189, s0
	ds_write_b16 v75, v1 offset:18224
	v_cvt_pk_bf16_f32 v1, v160, s0
	ds_write_b16 v75, v1 offset:18496
	v_cvt_pk_bf16_f32 v1, v161, s0
	ds_write_b16 v75, v1 offset:18768
	v_cvt_pk_bf16_f32 v1, v162, s0
	ds_write_b16 v75, v1 offset:19040
	v_cvt_pk_bf16_f32 v1, v163, s0
	ds_write_b16 v75, v1 offset:19312
	v_cvt_pk_bf16_f32 v1, v178, s0
	ds_write_b16 v75, v1 offset:19584
	v_cvt_pk_bf16_f32 v1, v179, s0
	ds_write_b16 v75, v1 offset:19856
	v_cvt_pk_bf16_f32 v1, v172, s0
	ds_write_b16 v75, v1 offset:20128
	v_cvt_pk_bf16_f32 v1, v173, s0
	ds_write_b16 v75, v1 offset:20400
	v_cvt_pk_bf16_f32 v1, v164, s0
	ds_write_b16 v75, v1 offset:20672
	v_cvt_pk_bf16_f32 v1, v165, s0
	ds_write_b16 v75, v1 offset:20944
	v_cvt_pk_bf16_f32 v1, v166, s0
	ds_write_b16 v75, v1 offset:21216
	v_cvt_pk_bf16_f32 v1, v167, s0
	ds_write_b16 v75, v1 offset:21488
	v_cvt_pk_bf16_f32 v1, v168, s0
	ds_write_b16 v75, v1 offset:21760
	v_cvt_pk_bf16_f32 v1, v169, s0
	ds_write_b16 v75, v1 offset:22032
	v_cvt_pk_bf16_f32 v1, v170, s0
	ds_write_b16 v75, v1 offset:22304
	v_cvt_pk_bf16_f32 v1, v171, s0
	ds_write_b16 v75, v1 offset:22576
	v_cvt_pk_bf16_f32 v1, v174, s0
	ds_write_b16 v75, v1 offset:22848
	v_cvt_pk_bf16_f32 v1, v175, s0
	ds_write_b16 v75, v1 offset:23120
	v_cvt_pk_bf16_f32 v1, v176, s0
	ds_write_b16 v75, v1 offset:23392
	v_cvt_pk_bf16_f32 v1, v177, s0
	ds_write_b16 v75, v1 offset:23664
	v_cvt_pk_bf16_f32 v1, v184, s0
	ds_write_b16 v75, v1 offset:23936
	v_cvt_pk_bf16_f32 v1, v185, s0
	ds_write_b16 v75, v1 offset:24208
	v_cvt_pk_bf16_f32 v1, v186, s0
	ds_write_b16 v75, v1 offset:24480
	v_cvt_pk_bf16_f32 v1, v187, s0
	ds_write_b16 v75, v1 offset:24752
	v_cvt_pk_bf16_f32 v1, v190, s0
	ds_write_b16 v75, v1 offset:25024
	v_cvt_pk_bf16_f32 v1, v191, s0
	ds_write_b16 v75, v1 offset:25296
	v_cvt_pk_bf16_f32 v1, v192, s0
	ds_write_b16 v75, v1 offset:25568
	v_cvt_pk_bf16_f32 v1, v193, s0
	ds_write_b16 v75, v1 offset:25840
	v_cvt_pk_bf16_f32 v1, v194, s0
	ds_write_b16 v75, v1 offset:26112
	v_cvt_pk_bf16_f32 v1, v195, s0
	ds_write_b16 v75, v1 offset:26384
	v_cvt_pk_bf16_f32 v1, v196, s0
	ds_write_b16 v75, v1 offset:26656
	v_cvt_pk_bf16_f32 v1, v197, s0
	ds_write_b16 v75, v1 offset:26928
	v_cvt_pk_bf16_f32 v1, v198, s0
	ds_write_b16 v75, v1 offset:27200
	v_cvt_pk_bf16_f32 v1, v199, s0
	ds_write_b16 v75, v1 offset:27472
	v_cvt_pk_bf16_f32 v1, v200, s0
	ds_write_b16 v75, v1 offset:27744
	v_cvt_pk_bf16_f32 v1, v201, s0
	ds_write_b16 v75, v1 offset:28016
	v_cvt_pk_bf16_f32 v1, v202, s0
	ds_write_b16 v75, v1 offset:28288
	v_cvt_pk_bf16_f32 v1, v203, s0
	ds_write_b16 v75, v1 offset:28560
	v_cvt_pk_bf16_f32 v1, v204, s0
	ds_write_b16 v75, v1 offset:28832
	v_cvt_pk_bf16_f32 v1, v205, s0
	ds_write_b16 v75, v1 offset:29104
	v_cvt_pk_bf16_f32 v1, v206, s0
	ds_write_b16 v75, v1 offset:29376
	v_cvt_pk_bf16_f32 v1, v207, s0
	ds_write_b16 v75, v1 offset:29648
	v_cvt_pk_bf16_f32 v1, v208, s0
	ds_write_b16 v75, v1 offset:29920
	v_cvt_pk_bf16_f32 v1, v209, s0
	ds_write_b16 v75, v1 offset:30192
	v_cvt_pk_bf16_f32 v1, v210, s0
	ds_write_b16 v75, v1 offset:30464
	v_cvt_pk_bf16_f32 v1, v211, s0
	ds_write_b16 v75, v1 offset:30736
	v_cvt_pk_bf16_f32 v1, v212, s0
	ds_write_b16 v75, v1 offset:31008
	v_cvt_pk_bf16_f32 v1, v213, s0
	ds_write_b16 v75, v1 offset:31280
	v_cvt_pk_bf16_f32 v1, v214, s0
	ds_write_b16 v75, v1 offset:31552
	v_cvt_pk_bf16_f32 v1, v215, s0
	ds_write_b16 v75, v1 offset:31824
	v_cvt_pk_bf16_f32 v1, v216, s0
	ds_write_b16 v75, v1 offset:32096
	v_cvt_pk_bf16_f32 v1, v217, s0
	ds_write_b16 v75, v1 offset:32368
	v_cvt_pk_bf16_f32 v1, v218, s0
	ds_write_b16 v75, v1 offset:32640
	v_cvt_pk_bf16_f32 v1, v219, s0
	ds_write_b16 v75, v1 offset:32912
	v_cvt_pk_bf16_f32 v1, v220, s0
	ds_write_b16 v75, v1 offset:33184
	v_cvt_pk_bf16_f32 v1, v221, s0
	ds_write_b16 v75, v1 offset:33456
	v_cvt_pk_bf16_f32 v1, v222, s0
	ds_write_b16 v75, v1 offset:33728
	v_cvt_pk_bf16_f32 v1, v223, s0
	ds_write_b16 v75, v1 offset:34000
	v_cvt_pk_bf16_f32 v1, v224, s0
	ds_write_b16 v75, v1 offset:34272
	v_cvt_pk_bf16_f32 v1, v225, s0
	ds_write_b16 v75, v1 offset:34544
